# v05 + gla_prep: flat->global, token-loop LDS reads pipelined (4 reads per token in flight)
# baseline (speedup 1.0000x reference)
.LBB0_525:
	s_ashr_i32 s16, s0, 2
	s_lshl_b32 s1, s16, 5
	v_writelane_b32 v254, s0, 23
	s_lshl_b32 s0, s16, 6
	s_addk_i32 s1, 0x1000
	s_cmpk_lt_i32 s16, 0x80
	v_mov_b32_e32 v25, v0
	s_cselect_b32 s0, s0, s1
	s_movk_i32 s1, 0x100
	s_cselect_b32 s73, 64, 32
	v_readfirstlane_b32 s55, v25
	v_cmp_gt_i32_e32 vcc, s1, v25
	s_and_saveexec_b64 s[4:5], vcc
	s_cbranch_execz .LBB0_529
	v_ashrrev_i32_e32 v6, 2, v25
	v_and_b32_e32 v1, 3, v25
	v_cmp_gt_i32_e32 vcc, s73, v6
	v_mov_b32_e32 v2, 0
	v_lshlrev_b32_e32 v8, 4, v1
	v_mov_b32_e32 v3, 0
	v_mov_b32_e32 v4, 0
	v_mov_b32_e32 v5, 0
	s_and_saveexec_b64 s[6:7], vcc
	s_cbranch_execz .LBB0_528
	s_ashr_i32 s1, s0, 31
	v_ashrrev_i32_e32 v7, 31, v6
	v_lshl_add_u64 v[2:3], v[6:7], 0, s[0:1]
	v_readlane_b32 s8, v253, 43
	v_lshlrev_b64 v[2:3], 6, v[2:3]
	v_readlane_b32 s9, v253, 44
	v_mov_b32_e32 v9, v34
	s_nop 0
	v_lshl_add_u64 v[2:3], s[8:9], 0, v[2:3]
	v_lshl_add_u64 v[2:3], v[2:3], 0, v[8:9]
	global_load_dwordx4 v[2:5], v[2:3], off

.LBB0_529:
	s_or_b64 exec, exec, s[4:5]
	s_and_b32 s1, s51, 0x300
	v_or_b32_sdwa v24, v25, s1 dst_sel:DWORD dst_unused:UNUSED_PAD src0_sel:BYTE_0 src1_sel:DWORD
	v_readlane_b32 s4, v252, 49
	v_lshlrev_b32_e32 v2, 2, v24
	v_mov_b32_e32 v3, v34
	v_readlane_b32 s5, v252, 50
	s_ashr_i32 s1, s0, 31
	s_lshl_b64 s[48:49], s[0:1], 11
	v_lshl_add_u64 v[20:21], s[4:5], 0, v[2:3]
	v_add_co_u32_e32 v6, vcc, 0x1000, v20
	s_nop 0
	global_load_dword v4, v2, s[4:5]
	v_addc_co_u32_e32 v7, vcc, 0, v21, vcc
	v_add_co_u32_e32 v8, vcc, 0x2000, v20
	global_load_dword v6, v[6:7], off
	s_nop 0
	v_addc_co_u32_e32 v9, vcc, 0, v21, vcc
	v_add_co_u32_e32 v10, vcc, 0x3000, v20
	global_load_dword v8, v[8:9], off
	s_nop 0
	v_addc_co_u32_e32 v11, vcc, 0, v21, vcc
	v_add_co_u32_e32 v12, vcc, 0x4000, v20
	global_load_dword v10, v[10:11], off
	s_nop 0
	v_addc_co_u32_e32 v13, vcc, 0, v21, vcc
	global_load_dword v5, v[12:13], off
	v_add_co_u32_e32 v12, vcc, 0x5000, v20
	v_readlane_b32 s4, v252, 51
	s_nop 0
	v_addc_co_u32_e32 v13, vcc, 0, v21, vcc
	global_load_dword v7, v[12:13], off
	v_add_co_u32_e32 v12, vcc, 0x6000, v20
	v_readlane_b32 s0, v252, 35
	s_nop 0
	v_addc_co_u32_e32 v13, vcc, 0, v21, vcc
	global_load_dword v9, v[12:13], off
	v_add_co_u32_e32 v12, vcc, 0x7000, v20
	v_readlane_b32 s5, v252, 52
	s_nop 0
	v_addc_co_u32_e32 v13, vcc, 0, v21, vcc
	global_load_dword v11, v[12:13], off
	v_add_co_u32_e32 v12, vcc, 0x8000, v20
	s_add_u32 s0, s0, s48
	s_nop 0
	v_addc_co_u32_e32 v13, vcc, 0, v21, vcc
	v_add_co_u32_e32 v14, vcc, 0x9000, v20
	global_load_dword v12, v[12:13], off
	s_nop 0
	v_addc_co_u32_e32 v15, vcc, 0, v21, vcc
	v_add_co_u32_e32 v16, vcc, 0xa000, v20
	global_load_dword v14, v[14:15], off
	s_nop 0
	v_addc_co_u32_e32 v17, vcc, 0, v21, vcc
	v_add_co_u32_e32 v18, vcc, 0xb000, v20
	global_load_dword v16, v[16:17], off
	s_nop 0
	v_addc_co_u32_e32 v19, vcc, 0, v21, vcc
	v_add_co_u32_e32 v22, vcc, 0xc000, v20
	global_load_dword v18, v[18:19], off
	s_nop 0
	v_addc_co_u32_e32 v23, vcc, 0, v21, vcc
	global_load_dword v13, v[22:23], off
	v_add_co_u32_e32 v22, vcc, 0xd000, v20
	v_readlane_b32 s1, v252, 36
	s_nop 0
	v_addc_co_u32_e32 v23, vcc, 0, v21, vcc
	global_load_dword v15, v[22:23], off
	v_add_co_u32_e32 v22, vcc, 0xe000, v20
	global_load_dword v26, v2, s[4:5]
	s_nop 0
	v_addc_co_u32_e32 v23, vcc, 0, v21, vcc
	v_add_co_u32_e32 v20, vcc, 0xf000, v20
	s_addc_u32 s1, s1, s49
	s_nop 0
	v_addc_co_u32_e32 v21, vcc, 0, v21, vcc
	v_lshlrev_b32_e32 v2, 1, v24
	global_load_dword v17, v[22:23], off
	global_load_dword v19, v[20:21], off
	v_lshl_add_u64 v[20:21], s[0:1], 0, v[2:3]
	v_readlane_b32 s0, v252, 39
	s_add_u32 s0, s0, s48
	v_readlane_b32 s1, v252, 41
	s_addc_u32 s1, s1, s49
	s_nop 0
	v_lshl_add_u64 v[22:23], s[0:1], 0, v[2:3]
	s_ashr_i32 s0, s55, 3
	s_and_b32 s38, s0, 0xffffffe0
	s_cmp_lt_i32 s38, s73
	s_cselect_b64 s[2:3], -1, 0
	v_writelane_b32 v255, s2, 45
	s_and_b64 s[4:5], s[2:3], exec
	s_cselect_b32 s4, s38, 0
	s_ashr_i32 s5, s4, 31
	v_writelane_b32 v255, s3, 46
	s_lshl_b64 s[2:3], s[4:5], 11
	s_or_b32 s72, s38, 1
	v_writelane_b32 v255, s2, 49
	s_cmp_lt_i32 s72, s73
	s_nop 0
	v_writelane_b32 v255, s3, 50
	s_cselect_b64 s[2:3], -1, 0
	v_writelane_b32 v255, s2, 3
	s_and_b64 s[4:5], s[2:3], exec
	s_cselect_b32 s4, s72, 0
	s_ashr_i32 s5, s4, 31
	v_writelane_b32 v255, s3, 4
	s_lshl_b64 s[2:3], s[4:5], 11
	s_or_b32 s40, s38, 2
	v_writelane_b32 v252, s2, 55
	s_cmp_lt_i32 s40, s73
	s_mov_b32 s58, s40
	v_writelane_b32 v252, s3, 56
	s_cselect_b64 s[2:3], -1, 0
	v_writelane_b32 v254, s2, 21
	s_and_b64 s[4:5], s[2:3], exec
	s_cselect_b32 s4, s40, 0
	s_ashr_i32 s5, s4, 31
	v_writelane_b32 v254, s3, 22
	s_lshl_b64 s[2:3], s[4:5], 11
	s_or_b32 s18, s38, 3
	s_cmp_lt_i32 s18, s73
	s_cselect_b64 s[14:15], -1, 0
	s_and_b64 s[4:5], s[14:15], exec
	s_cselect_b32 s4, s18, 0
	v_writelane_b32 v252, s2, 53
	s_ashr_i32 s5, s4, 31
	s_or_b32 s52, s38, 4
	v_writelane_b32 v252, s3, 54
	s_lshl_b64 s[2:3], s[4:5], 11
	v_writelane_b32 v252, s2, 57
	s_cmp_lt_i32 s52, s73
	s_nop 0
	v_writelane_b32 v252, s3, 58
	s_cselect_b64 s[2:3], -1, 0
	v_writelane_b32 v254, s2, 15
	s_and_b64 s[4:5], s[2:3], exec
	s_cselect_b32 s4, s52, 0
	s_ashr_i32 s5, s4, 31
	v_writelane_b32 v254, s3, 16
	s_lshl_b64 s[2:3], s[4:5], 11
	s_or_b32 s56, s38, 5
	s_cmp_lt_i32 s56, s73
	s_cselect_b64 s[10:11], -1, 0
	s_and_b64 s[4:5], s[10:11], exec
	s_cselect_b32 s4, s56, 0
	v_writelane_b32 v252, s2, 59
	s_ashr_i32 s5, s4, 31
	s_or_b32 s20, s38, 6
	v_writelane_b32 v252, s3, 60
	s_lshl_b64 s[2:3], s[4:5], 11
	s_cmp_lt_i32 s20, s73
	s_cselect_b64 s[12:13], -1, 0
	s_and_b64 s[4:5], s[12:13], exec
	s_cselect_b32 s4, s20, 0
	v_writelane_b32 v252, s2, 61
	s_ashr_i32 s5, s4, 31
	s_or_b32 s60, s38, 7
	v_writelane_b32 v252, s3, 62
	s_lshl_b64 s[2:3], s[4:5], 11
	s_cmp_lt_i32 s60, s73
	s_cselect_b64 s[22:23], -1, 0
	s_and_b64 s[4:5], s[22:23], exec
	s_cselect_b32 s4, s60, 0
	v_writelane_b32 v252, s2, 63
	s_ashr_i32 s5, s4, 31
	s_or_b32 s62, s38, 8
	v_writelane_b32 v255, s3, 0
	s_lshl_b64 s[2:3], s[4:5], 11
	v_writelane_b32 v255, s2, 5
	s_cmp_lt_i32 s62, s73
	v_writelane_b32 v252, s58, 33
	v_writelane_b32 v255, s3, 6
	s_cselect_b64 s[2:3], -1, 0
	v_writelane_b32 v255, s2, 23
	s_and_b64 s[4:5], s[2:3], exec
	s_cselect_b32 s4, s62, 0
	s_ashr_i32 s5, s4, 31
	v_writelane_b32 v255, s3, 24
	s_lshl_b64 s[2:3], s[4:5], 11
	s_or_b32 s64, s38, 9
	v_writelane_b32 v255, s2, 7
	s_cmp_lt_i32 s64, s73
	v_writelane_b32 v252, s59, 34
	v_writelane_b32 v255, s3, 8
	s_cselect_b64 s[2:3], -1, 0
	v_writelane_b32 v255, s2, 17
	s_and_b64 s[4:5], s[2:3], exec
	s_cselect_b32 s4, s64, 0
	s_ashr_i32 s5, s4, 31
	v_writelane_b32 v255, s3, 18
	s_lshl_b64 s[2:3], s[4:5], 11
	s_or_b32 s66, s38, 10
	v_writelane_b32 v255, s2, 11
	s_cmp_lt_i32 s66, s73
	s_mov_b32 s58, s18
	v_writelane_b32 v255, s3, 12
	s_cselect_b64 s[2:3], -1, 0
	v_writelane_b32 v255, s2, 27
	s_and_b64 s[4:5], s[2:3], exec
	s_cselect_b32 s4, s66, 0
	s_ashr_i32 s5, s4, 31
	v_writelane_b32 v255, s3, 28
	s_lshl_b64 s[2:3], s[4:5], 11
	s_or_b32 s68, s38, 11
	v_writelane_b32 v255, s2, 15
	s_cmp_lt_i32 s68, s73
	v_writelane_b32 v252, s58, 31
	v_writelane_b32 v255, s3, 16
	s_cselect_b64 s[2:3], -1, 0
	v_writelane_b32 v253, s2, 32
	s_and_b64 s[4:5], s[2:3], exec
	s_cselect_b32 s4, s68, 0
	s_ashr_i32 s5, s4, 31
	v_writelane_b32 v253, s3, 33
	s_lshl_b64 s[2:3], s[4:5], 11
	s_or_b32 s70, s38, 12
	s_cmp_lt_i32 s70, s73
	s_cselect_b64 s[28:29], -1, 0
	s_and_b64 s[4:5], s[28:29], exec
	s_cselect_b32 s4, s70, 0
	v_writelane_b32 v255, s2, 19
	s_ashr_i32 s5, s4, 31
	s_or_b32 s24, s38, 13
	v_writelane_b32 v255, s3, 20
	s_lshl_b64 s[2:3], s[4:5], 11
	v_writelane_b32 v255, s2, 21
	s_cmp_lt_i32 s24, s73
	v_writelane_b32 v252, s59, 32
	v_writelane_b32 v255, s3, 22
	s_cselect_b64 s[2:3], -1, 0
	v_writelane_b32 v255, s2, 1
	s_and_b64 s[4:5], s[2:3], exec
	s_cselect_b32 s4, s24, 0
	s_ashr_i32 s5, s4, 31
	v_writelane_b32 v255, s3, 2
	s_lshl_b64 s[2:3], s[4:5], 11
	s_or_b32 s44, s38, 14
	s_cmp_lt_i32 s44, s73
	s_cselect_b64 s[26:27], -1, 0
	s_and_b64 s[4:5], s[26:27], exec
	s_cselect_b32 s4, s44, 0
	v_writelane_b32 v255, s2, 25
	s_ashr_i32 s5, s4, 31
	s_or_b32 s74, s38, 15
	v_writelane_b32 v255, s3, 26
	s_lshl_b64 s[2:3], s[4:5], 11
	s_cmp_lt_i32 s74, s73
	s_cselect_b64 s[46:47], -1, 0
	s_and_b64 s[4:5], s[46:47], exec
	s_cselect_b32 s4, s74, 0
	v_writelane_b32 v255, s2, 29
	s_ashr_i32 s5, s4, 31
	s_or_b32 s76, s38, 16
	v_writelane_b32 v255, s3, 30
	s_lshl_b64 s[2:3], s[4:5], 11
	s_cmp_lt_i32 s76, s73
	s_cselect_b64 s[42:43], -1, 0
	s_and_b64 s[4:5], s[42:43], exec
	s_cselect_b32 s4, s76, 0
	v_writelane_b32 v255, s2, 31
	s_ashr_i32 s5, s4, 31
	s_or_b32 s78, s38, 17
	v_writelane_b32 v255, s3, 32
	s_lshl_b64 s[2:3], s[4:5], 11
	v_writelane_b32 v255, s2, 33
	s_cmp_lt_i32 s78, s73
	s_mov_b32 s58, s52
	v_writelane_b32 v255, s3, 34
	s_cselect_b64 s[2:3], -1, 0
	v_writelane_b32 v253, s2, 28
	s_and_b64 s[4:5], s[2:3], exec
	s_cselect_b32 s4, s78, 0
	s_ashr_i32 s5, s4, 31
	v_writelane_b32 v253, s3, 29
	s_lshl_b64 s[2:3], s[4:5], 11
	s_or_b32 s80, s38, 18
	s_cmp_lt_i32 s80, s73
	s_cselect_b64 vcc, -1, 0
	s_and_b64 s[4:5], vcc, exec
	s_cselect_b32 s4, s80, 0
	v_writelane_b32 v255, s2, 35
	s_ashr_i32 s5, s4, 31
	s_or_b32 s82, s38, 19
	v_writelane_b32 v255, s3, 36
	s_lshl_b64 s[2:3], s[4:5], 11
	s_cmp_lt_i32 s82, s73
	s_cselect_b64 s[36:37], -1, 0
	s_and_b64 s[4:5], s[36:37], exec
	s_cselect_b32 s4, s82, 0
	v_writelane_b32 v255, s2, 39
	s_ashr_i32 s5, s4, 31
	s_or_b32 s94, s38, 20
	v_writelane_b32 v255, s3, 40
	s_lshl_b64 s[2:3], s[4:5], 11
	s_cmp_lt_i32 s94, s73
	s_cselect_b64 s[34:35], -1, 0
	s_and_b64 s[4:5], s[34:35], exec
	s_cselect_b32 s4, s94, 0
	v_writelane_b32 v255, s2, 43
	s_ashr_i32 s5, s4, 31
	s_or_b32 s92, s38, 21
	v_writelane_b32 v255, s3, 44
	s_lshl_b64 s[2:3], s[4:5], 11
	s_cmp_lt_i32 s92, s73
	s_cselect_b64 s[30:31], -1, 0
	s_and_b64 s[4:5], s[30:31], exec
	s_cselect_b32 s4, s92, 0
	v_writelane_b32 v255, s2, 47
	s_ashr_i32 s5, s4, 31
	s_or_b32 s90, s38, 22
	v_writelane_b32 v255, s3, 48
	s_lshl_b64 s[2:3], s[4:5], 11
	v_writelane_b32 v255, s2, 51
	s_cmp_lt_i32 s90, s73
	s_nop 0
	v_writelane_b32 v255, s3, 52
	s_cselect_b64 s[2:3], -1, 0
	v_writelane_b32 v255, s2, 53
	s_and_b64 s[4:5], s[2:3], exec
	s_cselect_b32 s4, s90, 0
	s_ashr_i32 s5, s4, 31
	v_writelane_b32 v255, s3, 54
	s_lshl_b64 s[2:3], s[4:5], 11
	s_or_b32 s88, s38, 23
	v_writelane_b32 v255, s2, 55
	s_cmp_lt_i32 s88, s73
	s_nop 0
	v_writelane_b32 v255, s3, 56
	s_cselect_b64 s[2:3], -1, 0
	v_writelane_b32 v254, s2, 5
	s_and_b64 s[4:5], s[2:3], exec
	s_cselect_b32 s4, s88, 0
	s_ashr_i32 s5, s4, 31
	v_writelane_b32 v254, s3, 6
	s_lshl_b64 s[2:3], s[4:5], 11
	s_or_b32 s86, s38, 24
	v_writelane_b32 v255, s2, 59
	s_cmp_lt_i32 s86, s73
	s_nop 0
	v_writelane_b32 v255, s3, 60
	s_cselect_b64 s[2:3], -1, 0
	v_writelane_b32 v255, s2, 41
	s_and_b64 s[4:5], s[2:3], exec
	s_cselect_b32 s4, s86, 0
	s_ashr_i32 s5, s4, 31
	v_writelane_b32 v255, s3, 42
	s_lshl_b64 s[2:3], s[4:5], 11
	s_or_b32 s84, s38, 25
	v_writelane_b32 v254, s2, 9
	s_cmp_lt_i32 s84, s73
	s_nop 0
	v_writelane_b32 v254, s3, 10
	s_cselect_b64 s[2:3], -1, 0
	v_writelane_b32 v255, s2, 57
	s_and_b64 s[4:5], s[2:3], exec
	s_cselect_b32 s4, s84, 0
	s_ashr_i32 s5, s4, 31
	v_writelane_b32 v255, s3, 58
	s_lshl_b64 s[2:3], s[4:5], 11
	s_or_b32 s96, s38, 26
	v_writelane_b32 v255, s2, 63
	s_cmp_lt_i32 s96, s73
	s_nop 0
	v_writelane_b32 v254, s3, 0
	s_cselect_b64 s[2:3], -1, 0
	v_writelane_b32 v255, s2, 37
	s_and_b64 s[4:5], s[2:3], exec
	s_cselect_b32 s4, s96, 0
	s_ashr_i32 s5, s4, 31
	v_writelane_b32 v255, s3, 38
	s_lshl_b64 s[2:3], s[4:5], 11
	s_or_b32 s54, s38, 27
	v_writelane_b32 v254, s2, 1
	s_cmp_lt_i32 s54, s73
	s_nop 0
	v_writelane_b32 v254, s3, 2
	s_cselect_b64 s[2:3], -1, 0
	v_writelane_b32 v255, s2, 61
	s_and_b64 s[4:5], s[2:3], exec
	s_cselect_b32 s4, s54, 0
	s_ashr_i32 s5, s4, 31
	v_writelane_b32 v255, s3, 62
	s_lshl_b64 s[2:3], s[4:5], 11
	s_or_b32 s8, s38, 28
	v_writelane_b32 v254, s2, 3
	s_cmp_lt_i32 s8, s73
	s_nop 0
	v_writelane_b32 v254, s3, 4
	s_cselect_b64 s[2:3], -1, 0
	v_writelane_b32 v253, s2, 30
	s_and_b64 s[4:5], s[2:3], exec
	s_cselect_b32 s4, s8, 0
	s_ashr_i32 s5, s4, 31
	v_writelane_b32 v253, s3, 31
	s_lshl_b64 s[2:3], s[4:5], 11
	s_or_b32 s6, s38, 29
	v_writelane_b32 v254, s2, 7
	s_cmp_lt_i32 s6, s73
	s_nop 0
	v_writelane_b32 v254, s3, 8
	s_cselect_b64 s[2:3], -1, 0
	v_writelane_b32 v254, s2, 13
	s_and_b64 s[4:5], s[2:3], exec
	s_cselect_b32 s4, s6, 0
	s_ashr_i32 s5, s4, 31
	v_writelane_b32 v254, s3, 14
	s_lshl_b64 s[2:3], s[4:5], 11
	s_or_b32 s50, s38, 30
	v_writelane_b32 v254, s2, 11
	s_cmp_lt_i32 s50, s73
	s_nop 0
	v_writelane_b32 v254, s3, 12
	s_cselect_b64 s[2:3], -1, 0
	v_writelane_b32 v254, s2, 17
	s_and_b64 s[4:5], s[2:3], exec
	s_cselect_b32 s4, s50, 0
	v_writelane_b32 v254, s3, 18
	s_ashr_i32 s5, s4, 31
	s_lshl_b64 s[4:5], s[4:5], 11
	s_or_b32 s2, s0, 31
	v_writelane_b32 v254, s58, 25
	s_cmp_lt_i32 s2, s73
	s_cselect_b64 s[0:1], -1, 0
	v_writelane_b32 v254, s59, 26
	s_mov_b32 s58, s56
	v_writelane_b32 v254, s58, 27
	v_writelane_b32 v253, s0, 10
	s_nop 0
	v_writelane_b32 v254, s59, 28
	s_mov_b32 s58, s20
	v_writelane_b32 v253, s1, 11
	s_and_b64 s[0:1], s[0:1], exec
	v_writelane_b32 v254, s58, 31
	s_cselect_b32 s0, s2, 0
	s_lshl_b32 s71, s70, 6
	v_writelane_b32 v254, s59, 32
	s_lshl_b32 s59, s20, 6
	s_add_i32 s59, s59, 0
	s_mov_b32 s58, s60
	v_writelane_b32 v254, s58, 29
	s_add_i32 s9, s71, 0
	s_lshl_b32 s71, s24, 6
	v_writelane_b32 v254, s59, 30
	s_mov_b32 s58, s62
	v_writelane_b32 v254, s58, 33
	v_writelane_b32 v255, s9, 13
	s_add_i32 s9, s71, 0
	v_writelane_b32 v254, s59, 34
	s_mov_b32 s58, s64
	v_writelane_b32 v254, s58, 35
	s_lshl_b32 s71, s44, 6
	v_writelane_b32 v255, s9, 9
	v_writelane_b32 v254, s59, 36
	s_mov_b32 s58, s66
	v_writelane_b32 v254, s58, 37
	s_add_i32 s9, s71, 0
	s_lshl_b32 s71, s74, 6
	v_writelane_b32 v254, s59, 38
	s_mov_b32 s58, s68
	v_writelane_b32 v254, s58, 39
	s_ashr_i32 s1, s0, 31
	s_lshl_b64 s[0:1], s[0:1], 11
	v_writelane_b32 v254, s59, 40
	s_mov_b32 s58, s70
	v_writelane_b32 v254, s58, 41
	s_lshl_b32 s17, s38, 6
	s_add_i32 s7, s17, 0
	v_writelane_b32 v254, s59, 42
	s_mov_b32 s58, s24
	v_writelane_b32 v254, s58, 43
	s_lshl_b32 s17, s72, 6
	s_add_i32 s79, s17, 0
	v_writelane_b32 v254, s59, 44
	s_mov_b32 s58, s44
	v_writelane_b32 v254, s58, 45
	s_lshl_b32 s17, s40, 6
	s_add_i32 s3, s17, 0
	v_writelane_b32 v254, s59, 46
	v_writelane_b32 v254, s9, 49
	s_mov_b32 s58, s74
	v_writelane_b32 v254, s58, 47
	s_add_i32 s9, s71, 0
	s_lshl_b32 s71, s76, 6
	v_writelane_b32 v254, s59, 48
	v_writelane_b32 v254, s9, 52
	s_mov_b32 s58, s76
	v_writelane_b32 v254, s58, 50
	s_add_i32 s9, s71, 0
	s_lshl_b32 s71, s78, 6
	v_writelane_b32 v254, s59, 51
	v_writelane_b32 v254, s9, 55
	s_mov_b32 s58, s78
	v_writelane_b32 v254, s58, 53
	s_add_i32 s9, s71, 0
	s_lshl_b32 s71, s80, 6
	v_writelane_b32 v254, s59, 54
	v_writelane_b32 v254, s9, 58
	s_mov_b32 s58, s80
	v_writelane_b32 v254, s58, 56
	s_add_i32 s9, s71, 0
	s_lshl_b32 s71, s82, 6
	v_writelane_b32 v254, s59, 57
	v_writelane_b32 v254, s9, 61
	s_mov_b32 s58, s82
	v_writelane_b32 v254, s58, 59
	s_add_i32 s9, s71, 0
	s_lshl_b32 s71, s94, 6
	v_writelane_b32 v254, s59, 60
	s_mov_b32 s58, s94
	v_writelane_b32 v253, s9, 0
	v_writelane_b32 v254, s58, 62
	s_add_i32 s9, s71, 0
	v_writelane_b32 v253, s9, 3
	v_writelane_b32 v254, s59, 63
	s_mov_b32 s58, s92
	v_writelane_b32 v253, s58, 1
	s_lshl_b32 s71, s92, 6
	s_add_i32 s9, s71, 0
	v_writelane_b32 v253, s59, 2
	v_writelane_b32 v253, s9, 6
	s_mov_b32 s58, s90
	v_writelane_b32 v253, s58, 4
	s_lshl_b32 s71, s90, 6
	s_add_i32 s97, s71, 0
	v_writelane_b32 v253, s59, 5
	s_mov_b32 s58, s88
	v_writelane_b32 v253, s58, 8
	s_lshl_b32 s71, s88, 6
	s_add_i32 s95, s71, 0
	v_writelane_b32 v253, s59, 9
	s_mov_b32 s58, s86
	v_writelane_b32 v253, s58, 12
	s_lshl_b32 s71, s86, 6
	s_add_i32 s94, s71, 0
	v_writelane_b32 v253, s59, 13
	s_mov_b32 s58, s84
	v_writelane_b32 v253, s58, 14
	s_lshl_b32 s71, s84, 6
	s_add_i32 s93, s71, 0
	v_writelane_b32 v253, s59, 15
	s_mov_b32 s58, s96
	v_writelane_b32 v253, s58, 16
	s_lshl_b32 s71, s96, 6
	s_add_i32 s92, s71, 0
	v_writelane_b32 v253, s59, 17
	s_mov_b32 s58, s54
	s_lshl_b32 s71, s54, 6
	v_writelane_b32 v253, s58, 18
	s_add_i32 s9, s71, 0
	v_writelane_b32 v254, s9, 19
	v_writelane_b32 v253, s59, 19
	s_mov_b32 s58, s8
	s_lshl_b32 s71, s8, 6
	v_readlane_b32 s8, v255, 49
	v_readlane_b32 s9, v255, 50
	v_readlane_b32 s90, v255, 45
	v_readlane_b32 s91, v255, 46
	v_lshl_add_u64 v[28:29], v[20:21], 0, s[8:9]
	global_load_ushort v86, v[28:29], off
	v_lshl_add_u64 v[28:29], v[22:23], 0, s[8:9]
	v_readlane_b32 s8, v252, 55
	v_readlane_b32 s9, v252, 56
	global_load_ushort v1, v[28:29], off
	v_writelane_b32 v253, s58, 20
	v_lshl_add_u64 v[28:29], v[20:21], 0, s[8:9]
	global_load_ushort v84, v[28:29], off
	v_lshl_add_u64 v[28:29], v[22:23], 0, s[8:9]
	v_readlane_b32 s8, v252, 53
	v_readlane_b32 s9, v252, 54
	s_waitcnt vmcnt(0)
	global_load_ushort v88, v[28:29], off
	v_writelane_b32 v253, s59, 21
	v_lshl_add_u64 v[28:29], v[20:21], 0, s[8:9]
	global_load_ushort v82, v[28:29], off
	v_lshl_add_u64 v[28:29], v[22:23], 0, s[8:9]
	v_readlane_b32 s8, v252, 57
	v_readlane_b32 s9, v252, 58
	global_load_ushort v87, v[28:29], off
	s_add_i32 s96, s71, 0
	v_lshl_add_u64 v[28:29], v[20:21], 0, s[8:9]
	global_load_ushort v80, v[28:29], off
	v_lshl_add_u64 v[28:29], v[22:23], 0, s[8:9]
	v_readlane_b32 s8, v252, 59
	v_readlane_b32 s9, v252, 60
	global_load_ushort v85, v[28:29], off
	s_mov_b32 s58, s6
	v_lshl_add_u64 v[28:29], v[20:21], 0, s[8:9]
	global_load_ushort v79, v[28:29], off
	v_lshl_add_u64 v[28:29], v[22:23], 0, s[8:9]
	v_readlane_b32 s8, v252, 61
	v_readlane_b32 s9, v252, 62
	global_load_ushort v83, v[28:29], off
	s_lshl_b32 s71, s6, 6
	v_lshl_add_u64 v[28:29], v[20:21], 0, s[8:9]
	global_load_ushort v77, v[28:29], off
	v_lshl_add_u64 v[28:29], v[22:23], 0, s[8:9]
	v_readlane_b32 s8, v252, 63
	v_readlane_b32 s9, v255, 0
	global_load_ushort v81, v[28:29], off
	s_mov_b32 s6, 0xbfb8aa3b
	v_lshl_add_u64 v[28:29], v[20:21], 0, s[8:9]
	global_load_ushort v75, v[28:29], off
	v_lshl_add_u64 v[28:29], v[22:23], 0, s[8:9]
	v_readlane_b32 s8, v255, 5
	v_readlane_b32 s9, v255, 6
	global_load_ushort v78, v[28:29], off
	s_lshl_b32 s17, s18, 6
	v_lshl_add_u64 v[28:29], v[20:21], 0, s[8:9]
	global_load_ushort v73, v[28:29], off
	v_lshl_add_u64 v[28:29], v[22:23], 0, s[8:9]
	v_readlane_b32 s8, v255, 7
	v_readlane_b32 s9, v255, 8
	global_load_ushort v76, v[28:29], off
	s_add_i32 s17, s17, 0
	v_lshl_add_u64 v[28:29], v[20:21], 0, s[8:9]
	global_load_ushort v69, v[28:29], off
	v_lshl_add_u64 v[28:29], v[22:23], 0, s[8:9]
	v_readlane_b32 s8, v255, 11
	v_readlane_b32 s9, v255, 12
	global_load_ushort v74, v[28:29], off
	s_lshl_b32 s53, s52, 6
	v_lshl_add_u64 v[28:29], v[20:21], 0, s[8:9]
	global_load_ushort v70, v[28:29], off
	v_lshl_add_u64 v[28:29], v[22:23], 0, s[8:9]
	v_readlane_b32 s8, v255, 15
	v_readlane_b32 s9, v255, 16
	global_load_ushort v72, v[28:29], off
	s_add_i32 s53, s53, 0
	v_lshl_add_u64 v[28:29], v[20:21], 0, s[8:9]
	global_load_ushort v67, v[28:29], off
	v_lshl_add_u64 v[28:29], v[22:23], 0, s[8:9]
	v_readlane_b32 s8, v255, 19
	v_readlane_b32 s9, v255, 20
	global_load_ushort v71, v[28:29], off
	s_lshl_b32 s57, s56, 6
	v_lshl_add_u64 v[28:29], v[20:21], 0, s[8:9]
	global_load_ushort v65, v[28:29], off
	v_lshl_add_u64 v[28:29], v[22:23], 0, s[8:9]
	v_readlane_b32 s8, v255, 21
	v_readlane_b32 s9, v255, 22
	global_load_ushort v68, v[28:29], off
	s_add_i32 s57, s57, 0
	v_lshl_add_u64 v[28:29], v[20:21], 0, s[8:9]
	global_load_ushort v63, v[28:29], off
	v_lshl_add_u64 v[28:29], v[22:23], 0, s[8:9]
	v_readlane_b32 s8, v255, 25
	v_readlane_b32 s9, v255, 26
	global_load_ushort v66, v[28:29], off
	s_waitcnt vmcnt(0) lgkmcnt(0)
	v_lshlrev_b32_e32 v1, 16, v1
	v_lshl_add_u64 v[28:29], v[20:21], 0, s[8:9]
	global_load_ushort v61, v[28:29], off
	v_lshl_add_u64 v[28:29], v[22:23], 0, s[8:9]
	v_readlane_b32 s8, v255, 29
	v_readlane_b32 s9, v255, 30
	global_load_ushort v64, v[28:29], off
	v_cndmask_b32_e64 v89, 0, v1, s[90:91]
	v_lshl_add_u64 v[28:29], v[20:21], 0, s[8:9]
	global_load_ushort v59, v[28:29], off
	v_lshl_add_u64 v[28:29], v[22:23], 0, s[8:9]
	v_readlane_b32 s8, v255, 31
	v_readlane_b32 s9, v255, 32
	global_load_ushort v62, v[28:29], off
	v_mov_b32_e32 v1, s7
	v_lshl_add_u64 v[28:29], v[20:21], 0, s[8:9]
	global_load_ushort v57, v[28:29], off
	v_lshl_add_u64 v[28:29], v[22:23], 0, s[8:9]
	v_readlane_b32 s8, v255, 33
	v_readlane_b32 s9, v255, 34
	global_load_ushort v60, v[28:29], off
	s_mov_b32 s7, 0x800000
	v_lshl_add_u64 v[28:29], v[20:21], 0, s[8:9]
	global_load_ushort v43, v[28:29], off
	v_lshl_add_u64 v[28:29], v[22:23], 0, s[8:9]
	v_readlane_b32 s8, v255, 35
	v_readlane_b32 s9, v255, 36
	global_load_ushort v58, v[28:29], off
	v_writelane_b32 v253, s58, 22
	v_lshl_add_u64 v[28:29], v[20:21], 0, s[8:9]
	global_load_ushort v35, v[28:29], off
	v_lshl_add_u64 v[28:29], v[22:23], 0, s[8:9]
	v_readlane_b32 s8, v255, 39
	v_readlane_b32 s9, v255, 40
	global_load_ushort v50, v[28:29], off
	v_writelane_b32 v253, s59, 23
	v_lshl_add_u64 v[28:29], v[20:21], 0, s[8:9]
	global_load_ushort v36, v[28:29], off
	v_lshl_add_u64 v[28:29], v[22:23], 0, s[8:9]
	v_readlane_b32 s8, v255, 43
	v_readlane_b32 s9, v255, 44
	global_load_ushort v51, v[28:29], off
	s_mov_b32 s58, s50
	v_lshl_add_u64 v[28:29], v[20:21], 0, s[8:9]
	global_load_ushort v37, v[28:29], off
	v_lshl_add_u64 v[28:29], v[22:23], 0, s[8:9]
	v_readlane_b32 s8, v255, 47
	v_readlane_b32 s9, v255, 48
	global_load_ushort v52, v[28:29], off
	v_writelane_b32 v253, s58, 24
	v_lshl_add_u64 v[28:29], v[20:21], 0, s[8:9]
	global_load_ushort v38, v[28:29], off
	v_lshl_add_u64 v[28:29], v[22:23], 0, s[8:9]
	v_readlane_b32 s8, v255, 51
	v_readlane_b32 s9, v255, 52
	global_load_ushort v53, v[28:29], off
	v_writelane_b32 v253, s59, 25
	v_lshl_add_u64 v[28:29], v[20:21], 0, s[8:9]
	global_load_ushort v39, v[28:29], off
	v_lshl_add_u64 v[28:29], v[22:23], 0, s[8:9]
	v_readlane_b32 s8, v255, 55
	v_readlane_b32 s9, v255, 56
	global_load_ushort v54, v[28:29], off
	s_mov_b32 s58, s2
	v_lshl_add_u64 v[28:29], v[20:21], 0, s[8:9]
	global_load_ushort v40, v[28:29], off
	v_lshl_add_u64 v[28:29], v[22:23], 0, s[8:9]
	v_readlane_b32 s8, v255, 59
	v_readlane_b32 s9, v255, 60
	global_load_ushort v55, v[28:29], off
	v_writelane_b32 v253, s58, 26
	v_lshl_add_u64 v[28:29], v[20:21], 0, s[8:9]
	global_load_ushort v41, v[28:29], off
	v_lshl_add_u64 v[28:29], v[22:23], 0, s[8:9]
	v_readlane_b32 s8, v254, 9
	v_readlane_b32 s9, v254, 10
	global_load_ushort v56, v[28:29], off
	s_lshl_b32 s61, s60, 6
	v_lshl_add_u64 v[30:31], v[22:23], 0, s[8:9]
	global_load_ushort v49, v[30:31], off
	v_lshl_add_u64 v[28:29], v[20:21], 0, s[8:9]
	v_readlane_b32 s8, v255, 63
	v_readlane_b32 s9, v254, 0
	global_load_ushort v28, v[28:29], off
	s_add_i32 s61, s61, 0
	v_lshl_add_u64 v[30:31], v[20:21], 0, s[8:9]
	global_load_ushort v29, v[30:31], off
	v_lshl_add_u64 v[30:31], v[22:23], 0, s[8:9]
	v_readlane_b32 s8, v254, 1
	v_readlane_b32 s9, v254, 2
	global_load_ushort v44, v[30:31], off
	s_lshl_b32 s63, s62, 6
	v_lshl_add_u64 v[32:33], v[22:23], 0, s[8:9]
	global_load_ushort v45, v[32:33], off
	v_lshl_add_u64 v[30:31], v[20:21], 0, s[8:9]
	v_readlane_b32 s8, v254, 3
	v_readlane_b32 s9, v254, 4
	global_load_ushort v30, v[30:31], off
	s_add_i32 s63, s63, 0
	v_lshl_add_u64 v[32:33], v[20:21], 0, s[8:9]
	global_load_ushort v31, v[32:33], off
	v_lshl_add_u64 v[32:33], v[22:23], 0, s[8:9]
	v_readlane_b32 s8, v254, 7
	v_readlane_b32 s9, v254, 8
	global_load_ushort v46, v[32:33], off
	s_lshl_b32 s65, s64, 6
	v_lshl_add_u64 v[90:91], v[22:23], 0, s[8:9]
	global_load_ushort v47, v[90:91], off
	v_lshl_add_u64 v[32:33], v[20:21], 0, s[8:9]
	v_readlane_b32 s8, v254, 11
	v_readlane_b32 s9, v254, 12
	global_load_ushort v32, v[32:33], off
	s_add_i32 s65, s65, 0
	v_lshl_add_u64 v[90:91], v[20:21], 0, s[8:9]
	global_load_ushort v33, v[90:91], off
	v_lshl_add_u64 v[90:91], v[22:23], 0, s[8:9]
	global_load_ushort v48, v[90:91], off
	v_lshl_add_u64 v[90:91], v[20:21], 0, s[4:5]
	v_lshl_add_u64 v[20:21], v[20:21], 0, s[0:1]
	global_load_ushort v27, v[90:91], off
	s_mov_b32 s8, 0x3f317217
	global_load_ushort v20, v[20:21], off
	v_lshl_add_u64 v[90:91], v[22:23], 0, s[4:5]
	v_lshl_add_u64 v[22:23], v[22:23], 0, s[0:1]
	global_load_ushort v42, v[90:91], off
	global_load_ushort v21, v[22:23], off
	s_waitcnt lgkmcnt(0)
	s_barrier
	ds_read_b128 v[184:187], v1 offset:4096
	ds_read_b128 v[188:191], v1 offset:4112
	ds_read_b128 v[192:195], v1 offset:4128
	ds_read_b128 v[196:199], v1 offset:4144
	s_nop 0
	s_mov_b32 s9, 0x7f800000
	s_lshl_b32 s67, s66, 6
	s_add_i32 s67, s67, 0
	s_lshl_b32 s69, s68, 6
	s_waitcnt lgkmcnt(4)
	s_waitcnt lgkmcnt(3)
	v_mul_f32_e32 v22, v6, v185
	v_fmac_f32_e32 v22, v4, v184
	v_fmac_f32_e32 v22, v8, v186
	v_fmac_f32_e32 v22, v10, v187
	s_nop 0
	v_add_f32_e32 v22, v26, v22
	s_add_i32 s69, s69, 0
	v_writelane_b32 v253, s59, 27
	s_add_i32 s68, s71, 0
	s_nop 0
	s_waitcnt lgkmcnt(2)
	v_mul_f32_e32 v23, v7, v189
	v_fmac_f32_e32 v23, v5, v188
	v_fmac_f32_e32 v23, v9, v190
	v_fmac_f32_e32 v23, v11, v191
	s_nop 0
	v_add_f32_e32 v22, v22, v23
	s_lshl_b32 s71, s50, 6
	s_add_i32 s66, s71, 0
	s_lshl_b32 s71, s2, 6
	s_nop 0
	s_waitcnt lgkmcnt(1)
	v_mul_f32_e32 v23, v14, v193
	v_fmac_f32_e32 v23, v12, v192
	v_fmac_f32_e32 v23, v16, v194
	v_fmac_f32_e32 v23, v18, v195
	s_nop 0
	v_add_f32_e32 v22, v22, v23
	s_add_i32 s60, s71, 0
	v_readlane_b32 s82, v255, 3
	v_readlane_b32 s83, v255, 4
	s_nop 0
	s_waitcnt lgkmcnt(0)
	v_mul_f32_e32 v1, v15, v197
	v_fmac_f32_e32 v1, v13, v196
	v_fmac_f32_e32 v1, v17, v198
	v_fmac_f32_e32 v1, v19, v199
	v_add_f32_e32 v1, v22, v1
	v_max_f32_e64 v22, -v1, 0
	v_mul_f32_e64 v1, |v1|, s6
	v_exp_f32_e32 v1, v1
	s_mov_b64 s[80:81], s[14:15]
	s_mov_b64 s[76:77], s[10:11]
	s_and_b32 s71, s55, 0x3fffff00
	v_add_f32_e32 v1, 1.0, v1
	v_cmp_gt_f32_e64 s[0:1], s7, v1
	s_mov_b64 s[74:75], s[12:13]
	s_lshl_b32 s71, s71, 2
	v_cndmask_b32_e64 v23, 0, 32, s[0:1]
	v_ldexp_f32 v1, v1, v23
	v_log_f32_e32 v1, v1
	s_add_i32 s50, s71, 0
	s_mov_b64 s[70:71], s[22:23]
	s_cmpk_lt_u32 s55, 0x100
	v_mul_f32_e32 v23, 0x3f317217, v1
	v_fma_f32 v23, v1, s8, -v23
	v_fmac_f32_e32 v23, 0x3377d1cf, v1
	v_fmac_f32_e32 v23, 0x3f317217, v1
	v_cmp_lt_f32_e64 s[4:5], |v1|, s9
	v_readlane_b32 s55, v252, 43
	s_cselect_b64 s[88:89], -1, 0
	v_cndmask_b32_e64 v1, v1, v23, s[4:5]
	v_cndmask_b32_e64 v23, 0, v226, s[0:1]
	v_sub_f32_e32 v1, v1, v23
	v_mov_b32_e32 v23, s79
	ds_read_b128 v[184:187], v23 offset:4096
	ds_read_b128 v[188:191], v23 offset:4112
	ds_read_b128 v[192:195], v23 offset:4128
	ds_read_b128 v[196:199], v23 offset:4144
	s_nop 0
	v_add_f32_e32 v1, v22, v1
	v_mul_f32_e32 v1, 0xbd800000, v1
	v_cndmask_b32_e64 v22, 0, v1, s[90:91]
	v_add_f32_e32 v1, 0, v22
	s_nop 0
	s_waitcnt lgkmcnt(3)
	v_mul_f32_e32 v91, v6, v185
	v_fmac_f32_e32 v91, v4, v184
	v_fmac_f32_e32 v91, v8, v186
	v_fmac_f32_e32 v91, v10, v187
	v_add_f32_e32 v94, v26, v91
	s_nop 0
	v_readlane_b32 s78, v254, 15
	v_readlane_b32 s79, v254, 16
	s_add_u32 s84, s55, s48
	v_readlane_b32 s55, v252, 44
	s_nop 0
	s_waitcnt lgkmcnt(2)
	v_mul_f32_e32 v91, v7, v189
	v_fmac_f32_e32 v91, v5, v188
	v_fmac_f32_e32 v91, v9, v190
	v_fmac_f32_e32 v91, v11, v191
	v_add_f32_e32 v94, v94, v91
	s_nop 0
	s_addc_u32 s85, s55, s49
	v_readlane_b32 s55, v252, 45
	s_add_u32 s86, s55, s48
	s_mov_b64 s[54:55], s[28:29]
	s_nop 0
	s_waitcnt lgkmcnt(1)
	v_mul_f32_e32 v91, v14, v193
	v_fmac_f32_e32 v91, v12, v192
	v_fmac_f32_e32 v91, v16, v194
	v_fmac_f32_e32 v91, v18, v195
	v_add_f32_e32 v94, v94, v91
	s_nop 0
	v_readlane_b32 s48, v252, 46
	s_addc_u32 s87, s48, s49
	s_mov_b64 s[48:49], s[26:27]
	v_readlane_b32 s14, v253, 28
	s_nop 0
	s_waitcnt lgkmcnt(0)
	v_mul_f32_e32 v23, v15, v197
	v_fmac_f32_e32 v23, v13, v196
	v_fmac_f32_e32 v23, v17, v198
	v_fmac_f32_e32 v23, v19, v199
	v_add_f32_e32 v23, v94, v23
	v_max_f32_e64 v90, -v23, 0
	v_mul_f32_e64 v23, |v23|, s6
	v_exp_f32_e32 v23, v23
	v_mov_b32_e32 v94, s3
	ds_read_b128 v[184:187], v94 offset:4096
	ds_read_b128 v[188:191], v94 offset:4112
	ds_read_b128 v[192:195], v94 offset:4128
	ds_read_b128 v[196:199], v94 offset:4144
	v_readlane_b32 s2, v254, 21
	v_readlane_b32 s3, v254, 22
	v_add_f32_e32 v23, 1.0, v23
	v_cmp_gt_f32_e64 s[0:1], s7, v23
	v_readlane_b32 s15, v253, 29
	s_mov_b64 s[40:41], vcc
	v_cndmask_b32_e64 v91, 0, 32, s[0:1]
	v_ldexp_f32 v23, v23, v91
	v_log_f32_e32 v23, v23
	v_readlane_b32 s24, v255, 53
	v_readlane_b32 s25, v255, 54
	v_readlane_b32 s44, v254, 5
	v_mul_f32_e32 v91, 0x3f317217, v23
	v_fma_f32 v91, v23, s8, -v91
	v_fmac_f32_e32 v91, 0x3377d1cf, v23
	v_fmac_f32_e32 v91, 0x3f317217, v23
	v_cmp_lt_f32_e64 s[4:5], |v23|, s9
	v_readlane_b32 s45, v254, 6
	v_readlane_b32 s26, v255, 41
	v_cndmask_b32_e64 v23, v23, v91, s[4:5]
	v_cndmask_b32_e64 v91, 0, v226, s[0:1]
	v_sub_f32_e32 v23, v23, v91
	v_add_f32_e32 v23, v90, v23
	s_nop 0
	v_mul_f32_e32 v23, 0xbd800000, v23
	v_cndmask_b32_e64 v23, 0, v23, s[82:83]
	v_add_f32_e32 v1, v1, v23
	v_readlane_b32 s27, v255, 42
	s_nop 0
	s_waitcnt lgkmcnt(3)
	v_mul_f32_e32 v91, v6, v185
	v_fmac_f32_e32 v91, v4, v184
	v_fmac_f32_e32 v91, v8, v186
	v_fmac_f32_e32 v91, v10, v187
	v_add_f32_e32 v95, v26, v91
	s_nop 0
	v_readlane_b32 s28, v255, 57
	v_readlane_b32 s29, v255, 58
	v_readlane_b32 s22, v255, 37
	v_readlane_b32 s23, v255, 38
	s_nop 0
	s_waitcnt lgkmcnt(2)
	v_mul_f32_e32 v91, v7, v189
	v_fmac_f32_e32 v91, v5, v188
	v_fmac_f32_e32 v91, v9, v190
	v_fmac_f32_e32 v91, v11, v191
	v_add_f32_e32 v95, v95, v91
	s_nop 0
	v_readlane_b32 s10, v255, 61
	v_readlane_b32 s11, v255, 62
	v_readlane_b32 s18, v253, 30
	v_readlane_b32 s19, v253, 31
	s_nop 0
	s_waitcnt lgkmcnt(1)
	v_mul_f32_e32 v91, v14, v193
	v_fmac_f32_e32 v91, v12, v192
	v_fmac_f32_e32 v91, v16, v194
	v_fmac_f32_e32 v91, v18, v195
	v_add_f32_e32 v95, v95, v91
	s_nop 0
	v_readlane_b32 s20, v254, 13
	v_readlane_b32 s21, v254, 14
	v_readlane_b32 s12, v254, 17
	v_readlane_b32 s13, v254, 18
	s_nop 0
	s_waitcnt lgkmcnt(0)
	v_mul_f32_e32 v91, v15, v197
	v_fmac_f32_e32 v91, v13, v196
	v_fmac_f32_e32 v91, v17, v198
	v_fmac_f32_e32 v91, v19, v199
	v_add_f32_e32 v90, v95, v91
	v_max_f32_e64 v91, -v90, 0
	v_mul_f32_e64 v90, |v90|, s6
	v_exp_f32_e32 v90, v90
	s_ashr_i32 s39, s38, 31
	s_cmp_ge_i32 s38, s73
	v_add_f32_e32 v90, 1.0, v90
	v_cmp_gt_f32_e64 s[0:1], s7, v90
	s_nop 1
	v_cndmask_b32_e64 v92, 0, 32, s[0:1]
	v_ldexp_f32 v90, v90, v92
	v_log_f32_e32 v90, v90
	s_nop 0
	v_mul_f32_e32 v92, 0x3f317217, v90
	v_fma_f32 v92, v90, s8, -v92
	v_fmac_f32_e32 v92, 0x3377d1cf, v90
	v_fmac_f32_e32 v92, 0x3f317217, v90
	v_cmp_lt_f32_e64 s[4:5], |v90|, s9
	s_nop 1
	v_cndmask_b32_e64 v90, v90, v92, s[4:5]
	v_cndmask_b32_e64 v92, 0, v226, s[0:1]
	v_sub_f32_e32 v90, v90, v92
	v_add_f32_e32 v90, v91, v90
	v_mov_b32_e32 v91, s17
	ds_read_b128 v[184:187], v91 offset:4096
	ds_read_b128 v[188:191], v91 offset:4112
	ds_read_b128 v[192:195], v91 offset:4128
	ds_read_b128 v[196:199], v91 offset:4144
	s_nop 0
	v_mul_f32_e32 v90, 0xbd800000, v90
	v_cndmask_b32_e64 v90, 0, v90, s[2:3]
	v_add_f32_e32 v1, v1, v90
	s_nop 0
	s_waitcnt lgkmcnt(3)
	v_mul_f32_e32 v93, v6, v185
	v_fmac_f32_e32 v93, v4, v184
	v_fmac_f32_e32 v93, v8, v186
	v_fmac_f32_e32 v93, v10, v187
	v_add_f32_e32 v96, v26, v93
	s_nop 0
	s_nop 0
	s_waitcnt lgkmcnt(2)
	v_mul_f32_e32 v93, v7, v189
	v_fmac_f32_e32 v93, v5, v188
	v_fmac_f32_e32 v93, v9, v190
	v_fmac_f32_e32 v93, v11, v191
	v_add_f32_e32 v96, v96, v93
	s_nop 0
	s_nop 0
	s_waitcnt lgkmcnt(1)
	v_mul_f32_e32 v93, v14, v193
	v_fmac_f32_e32 v93, v12, v192
	v_fmac_f32_e32 v93, v16, v194
	v_fmac_f32_e32 v93, v18, v195
	v_add_f32_e32 v96, v96, v93
	s_nop 0
	s_nop 0
	s_waitcnt lgkmcnt(0)
	v_mul_f32_e32 v91, v15, v197
	v_fmac_f32_e32 v91, v13, v196
	v_fmac_f32_e32 v91, v17, v198
	v_fmac_f32_e32 v91, v19, v199
	v_add_f32_e32 v91, v96, v91
	v_max_f32_e64 v92, -v91, 0
	v_mul_f32_e64 v91, |v91|, s6
	v_exp_f32_e32 v91, v91
	v_mov_b32_e32 v96, s53
	ds_read_b128 v[184:187], v96 offset:4096
	ds_read_b128 v[188:191], v96 offset:4112
	ds_read_b128 v[192:195], v96 offset:4128
	ds_read_b128 v[196:199], v96 offset:4144
	v_readlane_b32 s52, v255, 1
	v_readlane_b32 s53, v255, 2
	v_add_f32_e32 v91, 1.0, v91
	v_cmp_gt_f32_e64 s[0:1], s7, v91
	s_nop 1
	v_cndmask_b32_e64 v93, 0, 32, s[0:1]
	v_ldexp_f32 v91, v91, v93
	v_log_f32_e32 v91, v91
	s_nop 0
	v_mul_f32_e32 v93, 0x3f317217, v91
	v_fma_f32 v93, v91, s8, -v93
	v_fmac_f32_e32 v93, 0x3377d1cf, v91
	v_fmac_f32_e32 v93, 0x3f317217, v91
	v_cmp_lt_f32_e64 s[4:5], |v91|, s9
	s_nop 1
	v_cndmask_b32_e64 v91, v91, v93, s[4:5]
	v_cndmask_b32_e64 v93, 0, v226, s[0:1]
	v_sub_f32_e32 v91, v91, v93
	v_add_f32_e32 v91, v92, v91
	s_nop 0
	v_mul_f32_e32 v91, 0xbd800000, v91
	v_cndmask_b32_e64 v91, 0, v91, s[80:81]
	v_add_f32_e32 v1, v1, v91
	s_nop 0
	s_waitcnt lgkmcnt(3)
	v_mul_f32_e32 v93, v6, v185
	v_fmac_f32_e32 v93, v4, v184
	v_fmac_f32_e32 v93, v8, v186
	v_fmac_f32_e32 v93, v10, v187
	v_add_f32_e32 v97, v26, v93
	s_nop 0
	s_nop 0
	s_waitcnt lgkmcnt(2)
	v_mul_f32_e32 v93, v7, v189
	v_fmac_f32_e32 v93, v5, v188
	v_fmac_f32_e32 v93, v9, v190
	v_fmac_f32_e32 v93, v11, v191
	v_add_f32_e32 v97, v97, v93
	s_nop 0
	s_nop 0
	s_waitcnt lgkmcnt(1)
	v_mul_f32_e32 v93, v14, v193
	v_fmac_f32_e32 v93, v12, v192
	v_fmac_f32_e32 v93, v16, v194
	v_fmac_f32_e32 v93, v18, v195
	v_add_f32_e32 v97, v97, v93
	s_nop 0
	s_nop 0
	s_waitcnt lgkmcnt(0)
	v_mul_f32_e32 v93, v15, v197
	v_fmac_f32_e32 v93, v13, v196
	v_fmac_f32_e32 v93, v17, v198
	v_fmac_f32_e32 v93, v19, v199
	v_add_f32_e32 v92, v97, v93
	v_max_f32_e64 v93, -v92, 0
	v_mul_f32_e64 v92, |v92|, s6
	v_exp_f32_e32 v92, v92
	s_nop 0
	v_add_f32_e32 v92, 1.0, v92
	v_cmp_gt_f32_e64 s[0:1], s7, v92
	s_nop 1
	v_cndmask_b32_e64 v94, 0, 32, s[0:1]
	v_ldexp_f32 v92, v92, v94
	v_log_f32_e32 v92, v92
	s_nop 0
	v_mul_f32_e32 v94, 0x3f317217, v92
	v_fma_f32 v94, v92, s8, -v94
	v_fmac_f32_e32 v94, 0x3377d1cf, v92
	v_fmac_f32_e32 v94, 0x3f317217, v92
	v_cmp_lt_f32_e64 s[4:5], |v92|, s9
	s_nop 1
	v_cndmask_b32_e64 v92, v92, v94, s[4:5]
	v_cndmask_b32_e64 v94, 0, v226, s[0:1]
	v_sub_f32_e32 v92, v92, v94
	v_add_f32_e32 v92, v93, v92
	v_mov_b32_e32 v93, s57
	ds_read_b128 v[184:187], v93 offset:4096
	ds_read_b128 v[188:191], v93 offset:4112
	ds_read_b128 v[192:195], v93 offset:4128
	ds_read_b128 v[196:199], v93 offset:4144
	s_nop 0
	v_mul_f32_e32 v92, 0xbd800000, v92
	v_cndmask_b32_e64 v92, 0, v92, s[78:79]
	v_add_f32_e32 v1, v1, v92
	v_readlane_b32 s56, v253, 32
	s_nop 0
	s_waitcnt lgkmcnt(3)
	v_mul_f32_e32 v95, v6, v185
	v_fmac_f32_e32 v95, v4, v184
	v_fmac_f32_e32 v95, v8, v186
	v_fmac_f32_e32 v95, v10, v187
	v_add_f32_e32 v98, v26, v95
	s_nop 0
	v_readlane_b32 s57, v253, 33
	s_nop 0
	s_waitcnt lgkmcnt(2)
	v_mul_f32_e32 v95, v7, v189
	v_fmac_f32_e32 v95, v5, v188
	v_fmac_f32_e32 v95, v9, v190
	v_fmac_f32_e32 v95, v11, v191
	v_add_f32_e32 v98, v98, v95
	s_nop 0
	s_nop 0
	s_waitcnt lgkmcnt(1)
	v_mul_f32_e32 v95, v14, v193
	v_fmac_f32_e32 v95, v12, v192
	v_fmac_f32_e32 v95, v16, v194
	v_fmac_f32_e32 v95, v18, v195
	v_add_f32_e32 v98, v98, v95
	s_nop 0
	s_nop 0
	s_waitcnt lgkmcnt(0)
	v_mul_f32_e32 v93, v15, v197
	v_fmac_f32_e32 v93, v13, v196
	v_fmac_f32_e32 v93, v17, v198
	v_fmac_f32_e32 v93, v19, v199
	v_add_f32_e32 v93, v98, v93
	v_max_f32_e64 v94, -v93, 0
	v_mul_f32_e64 v93, |v93|, s6
	v_exp_f32_e32 v93, v93
	v_mov_b32_e32 v98, s59
	ds_read_b128 v[184:187], v98 offset:4096
	ds_read_b128 v[188:191], v98 offset:4112
	ds_read_b128 v[192:195], v98 offset:4128
	ds_read_b128 v[196:199], v98 offset:4144
	v_readlane_b32 s58, v255, 27
	v_readlane_b32 s59, v255, 28
	v_add_f32_e32 v93, 1.0, v93
	v_cmp_gt_f32_e64 s[0:1], s7, v93
	s_nop 1
	v_cndmask_b32_e64 v95, 0, 32, s[0:1]
	v_ldexp_f32 v93, v93, v95
	v_log_f32_e32 v93, v93
	s_nop 0
	v_mul_f32_e32 v95, 0x3f317217, v93
	v_fma_f32 v95, v93, s8, -v95
	v_fmac_f32_e32 v95, 0x3377d1cf, v93
	v_fmac_f32_e32 v95, 0x3f317217, v93
	v_cmp_lt_f32_e64 s[4:5], |v93|, s9
	s_nop 1
	v_cndmask_b32_e64 v93, v93, v95, s[4:5]
	v_cndmask_b32_e64 v95, 0, v226, s[0:1]
	v_sub_f32_e32 v93, v93, v95
	v_add_f32_e32 v93, v94, v93
	s_nop 0
	v_mul_f32_e32 v93, 0xbd800000, v93
	v_cndmask_b32_e64 v93, 0, v93, s[76:77]
	v_add_f32_e32 v1, v1, v93
	s_nop 0
	s_waitcnt lgkmcnt(3)
	v_mul_f32_e32 v95, v6, v185
	v_fmac_f32_e32 v95, v4, v184
	v_fmac_f32_e32 v95, v8, v186
	v_fmac_f32_e32 v95, v10, v187
	v_add_f32_e32 v99, v26, v95
	s_nop 0
	s_nop 0
	s_waitcnt lgkmcnt(2)
	v_mul_f32_e32 v95, v7, v189
	v_fmac_f32_e32 v95, v5, v188
	v_fmac_f32_e32 v95, v9, v190
	v_fmac_f32_e32 v95, v11, v191
	v_add_f32_e32 v99, v99, v95
	s_nop 0
	s_nop 0
	s_waitcnt lgkmcnt(1)
	v_mul_f32_e32 v95, v14, v193
	v_fmac_f32_e32 v95, v12, v192
	v_fmac_f32_e32 v95, v16, v194
	v_fmac_f32_e32 v95, v18, v195
	v_add_f32_e32 v99, v99, v95
	s_nop 0
	s_nop 0
	s_waitcnt lgkmcnt(0)
	v_mul_f32_e32 v95, v15, v197
	v_fmac_f32_e32 v95, v13, v196
	v_fmac_f32_e32 v95, v17, v198
	v_fmac_f32_e32 v95, v19, v199
	v_add_f32_e32 v94, v99, v95
	v_max_f32_e64 v95, -v94, 0
	v_mul_f32_e64 v94, |v94|, s6
	v_exp_f32_e32 v94, v94
	s_nop 0
	v_add_f32_e32 v94, 1.0, v94
	v_cmp_gt_f32_e64 s[0:1], s7, v94
	s_nop 1
	v_cndmask_b32_e64 v96, 0, 32, s[0:1]
	v_ldexp_f32 v94, v94, v96
	v_log_f32_e32 v94, v94
	s_nop 0
	v_mul_f32_e32 v96, 0x3f317217, v94
	v_fma_f32 v96, v94, s8, -v96
	v_fmac_f32_e32 v96, 0x3377d1cf, v94
	v_fmac_f32_e32 v96, 0x3f317217, v94
	v_cmp_lt_f32_e64 s[4:5], |v94|, s9
	s_nop 1
	v_cndmask_b32_e64 v94, v94, v96, s[4:5]
	v_cndmask_b32_e64 v96, 0, v226, s[0:1]
	v_sub_f32_e32 v94, v94, v96
	v_add_f32_e32 v94, v95, v94
	v_mov_b32_e32 v95, s61
	ds_read_b128 v[184:187], v95 offset:4096
	ds_read_b128 v[188:191], v95 offset:4112
	ds_read_b128 v[192:195], v95 offset:4128
	ds_read_b128 v[196:199], v95 offset:4144
	s_nop 0
	s_nop 0
	s_nop 0
	s_nop 0
	v_mul_f32_e32 v94, 0xbd800000, v94
	s_nop 0
	s_waitcnt lgkmcnt(3)
	v_mul_f32_e32 v95, v6, v185
	v_fmac_f32_e32 v95, v4, v184
	s_waitcnt lgkmcnt(2)
	v_mul_f32_e32 v96, v7, v189
	v_fmac_f32_e32 v95, v8, v186
	v_fmac_f32_e32 v96, v5, v188
	v_fmac_f32_e32 v95, v10, v187
	v_fmac_f32_e32 v96, v9, v190
	v_add_f32_e32 v95, v26, v95
	v_fmac_f32_e32 v96, v11, v191
	v_add_f32_e32 v95, v95, v96
	s_waitcnt lgkmcnt(1)
	v_mul_f32_e32 v96, v14, v193
	v_fmac_f32_e32 v96, v12, v192
	v_fmac_f32_e32 v96, v16, v194
	v_fmac_f32_e32 v96, v18, v195
	v_add_f32_e32 v95, v95, v96
	s_waitcnt lgkmcnt(0)
	v_mul_f32_e32 v96, v15, v197
	v_fmac_f32_e32 v96, v13, v196
	v_fmac_f32_e32 v96, v17, v198
	v_fmac_f32_e32 v96, v19, v199
	v_add_f32_e32 v95, v95, v96
	v_max_f32_e64 v96, -v95, 0
	v_mul_f32_e64 v95, |v95|, s6
	v_exp_f32_e32 v95, v95
	v_mov_b32_e32 v108, s63
	ds_read_b128 v[184:187], v108 offset:4096
	ds_read_b128 v[188:191], v108 offset:4112
	ds_read_b128 v[192:195], v108 offset:4128
	ds_read_b128 v[196:199], v108 offset:4144
	v_cndmask_b32_e64 v94, 0, v94, s[74:75]
	v_readlane_b32 s62, v255, 23
	v_add_f32_e32 v95, 1.0, v95
	v_cmp_gt_f32_e64 s[0:1], s7, v95
	v_add_f32_e32 v1, v1, v94
	v_readlane_b32 s63, v255, 24
	v_cndmask_b32_e64 v97, 0, 32, s[0:1]
	v_ldexp_f32 v95, v95, v97
	v_log_f32_e32 v95, v95
	s_nop 0
	v_mul_f32_e32 v97, 0x3f317217, v95
	v_fma_f32 v97, v95, s8, -v97
	v_fmac_f32_e32 v97, 0x3377d1cf, v95
	v_fmac_f32_e32 v97, 0x3f317217, v95
	v_cmp_lt_f32_e64 s[4:5], |v95|, s9
	s_nop 1
	v_cndmask_b32_e64 v95, v95, v97, s[4:5]
	v_cndmask_b32_e64 v97, 0, v226, s[0:1]
	v_sub_f32_e32 v95, v95, v97
	v_add_f32_e32 v95, v96, v95
	s_nop 0
	s_nop 0
	s_nop 0
	s_nop 0
	v_mul_f32_e32 v95, 0xbd800000, v95
	s_nop 0
	s_waitcnt lgkmcnt(3)
	v_mul_f32_e32 v97, v6, v185
	v_fmac_f32_e32 v97, v4, v184
	v_fmac_f32_e32 v97, v8, v186
	v_fmac_f32_e32 v97, v10, v187
	v_add_f32_e32 v96, v26, v97
	s_waitcnt lgkmcnt(2)
	v_mul_f32_e32 v97, v7, v189
	v_fmac_f32_e32 v97, v5, v188
	v_fmac_f32_e32 v97, v9, v190
	v_fmac_f32_e32 v97, v11, v191
	v_add_f32_e32 v96, v96, v97
	s_waitcnt lgkmcnt(1)
	v_mul_f32_e32 v97, v14, v193
	v_fmac_f32_e32 v97, v12, v192
	v_fmac_f32_e32 v97, v16, v194
	v_fmac_f32_e32 v97, v18, v195
	v_add_f32_e32 v96, v96, v97
	s_waitcnt lgkmcnt(0)
	v_mul_f32_e32 v97, v15, v197
	v_fmac_f32_e32 v97, v13, v196
	v_fmac_f32_e32 v97, v17, v198
	v_fmac_f32_e32 v97, v19, v199
	v_add_f32_e32 v96, v96, v97
	v_max_f32_e64 v97, -v96, 0
	v_mul_f32_e64 v96, |v96|, s6
	v_exp_f32_e32 v96, v96
	v_cndmask_b32_e64 v95, 0, v95, s[70:71]
	v_add_f32_e32 v1, v1, v95
	v_add_f32_e32 v96, 1.0, v96
	v_cmp_gt_f32_e64 s[0:1], s7, v96
	s_nop 1
	v_cndmask_b32_e64 v98, 0, 32, s[0:1]
	v_ldexp_f32 v96, v96, v98
	v_log_f32_e32 v96, v96
	s_nop 0
	v_mul_f32_e32 v98, 0x3f317217, v96
	v_fma_f32 v98, v96, s8, -v98
	v_fmac_f32_e32 v98, 0x3377d1cf, v96
	v_fmac_f32_e32 v98, 0x3f317217, v96
	v_cmp_lt_f32_e64 s[4:5], |v96|, s9
	s_nop 1
	v_cndmask_b32_e64 v96, v96, v98, s[4:5]
	v_cndmask_b32_e64 v98, 0, v226, s[0:1]
	v_sub_f32_e32 v96, v96, v98
	v_add_f32_e32 v96, v97, v96
	v_mov_b32_e32 v97, s65
	ds_read_b128 v[184:187], v97 offset:4096
	ds_read_b128 v[188:191], v97 offset:4112
	ds_read_b128 v[192:195], v97 offset:4128
	ds_read_b128 v[196:199], v97 offset:4144
	s_nop 0
	s_nop 0
	s_nop 0
	s_nop 0
	v_mul_f32_e32 v96, 0xbd800000, v96
	s_nop 0
	s_waitcnt lgkmcnt(3)
	v_mul_f32_e32 v97, v6, v185
	v_fmac_f32_e32 v97, v4, v184
	s_waitcnt lgkmcnt(2)
	v_mul_f32_e32 v98, v7, v189
	v_fmac_f32_e32 v97, v8, v186
	v_fmac_f32_e32 v98, v5, v188
	v_fmac_f32_e32 v97, v10, v187
	v_fmac_f32_e32 v98, v9, v190
	v_add_f32_e32 v97, v26, v97
	v_fmac_f32_e32 v98, v11, v191
	v_add_f32_e32 v97, v97, v98
	s_waitcnt lgkmcnt(1)
	v_mul_f32_e32 v98, v14, v193
	v_fmac_f32_e32 v98, v12, v192
	v_fmac_f32_e32 v98, v16, v194
	v_fmac_f32_e32 v98, v18, v195
	v_add_f32_e32 v97, v97, v98
	s_waitcnt lgkmcnt(0)
	v_mul_f32_e32 v98, v15, v197
	v_fmac_f32_e32 v98, v13, v196
	v_fmac_f32_e32 v98, v17, v198
	v_fmac_f32_e32 v98, v19, v199
	v_add_f32_e32 v97, v97, v98
	v_max_f32_e64 v98, -v97, 0
	v_mul_f32_e64 v97, |v97|, s6
	v_exp_f32_e32 v97, v97
	v_mov_b32_e32 v110, s67
	ds_read_b128 v[184:187], v110 offset:4096
	ds_read_b128 v[188:191], v110 offset:4112
	ds_read_b128 v[192:195], v110 offset:4128
	ds_read_b128 v[196:199], v110 offset:4144
	v_readlane_b32 s64, v255, 17
	v_cndmask_b32_e64 v96, 0, v96, s[62:63]
	v_add_f32_e32 v97, 1.0, v97
	v_cmp_gt_f32_e64 s[0:1], s7, v97
	v_readlane_b32 s65, v255, 18
	v_add_f32_e32 v1, v1, v96
	v_cndmask_b32_e64 v99, 0, 32, s[0:1]
	v_ldexp_f32 v97, v97, v99
	v_log_f32_e32 v97, v97
	s_nop 0
	v_mul_f32_e32 v99, 0x3f317217, v97
	v_fma_f32 v99, v97, s8, -v99
	v_fmac_f32_e32 v99, 0x3377d1cf, v97
	v_fmac_f32_e32 v99, 0x3f317217, v97
	v_cmp_lt_f32_e64 s[4:5], |v97|, s9
	s_nop 1
	v_cndmask_b32_e64 v97, v97, v99, s[4:5]
	v_cndmask_b32_e64 v99, 0, v226, s[0:1]
	v_sub_f32_e32 v97, v97, v99
	v_add_f32_e32 v97, v98, v97
	s_nop 0
	s_nop 0
	s_nop 0
	s_nop 0
	v_mul_f32_e32 v97, 0xbd800000, v97
	s_nop 0
	s_waitcnt lgkmcnt(3)
	v_mul_f32_e32 v99, v6, v185
	v_fmac_f32_e32 v99, v4, v184
	v_fmac_f32_e32 v99, v8, v186
	v_fmac_f32_e32 v99, v10, v187
	v_add_f32_e32 v98, v26, v99
	s_waitcnt lgkmcnt(2)
	v_mul_f32_e32 v99, v7, v189
	v_fmac_f32_e32 v99, v5, v188
	v_fmac_f32_e32 v99, v9, v190
	v_fmac_f32_e32 v99, v11, v191
	v_add_f32_e32 v98, v98, v99
	s_waitcnt lgkmcnt(1)
	v_mul_f32_e32 v99, v14, v193
	v_fmac_f32_e32 v99, v12, v192
	v_fmac_f32_e32 v99, v16, v194
	v_fmac_f32_e32 v99, v18, v195
	v_add_f32_e32 v98, v98, v99
	s_waitcnt lgkmcnt(0)
	v_mul_f32_e32 v99, v15, v197
	v_fmac_f32_e32 v99, v13, v196
	v_fmac_f32_e32 v99, v17, v198
	v_fmac_f32_e32 v99, v19, v199
	v_add_f32_e32 v98, v98, v99
	v_max_f32_e64 v99, -v98, 0
	v_mul_f32_e64 v98, |v98|, s6
	v_exp_f32_e32 v98, v98
	v_cndmask_b32_e64 v97, 0, v97, s[64:65]
	v_add_f32_e32 v1, v1, v97
	v_add_f32_e32 v98, 1.0, v98
	v_cmp_gt_f32_e64 s[0:1], s7, v98
	s_nop 1
	v_cndmask_b32_e64 v100, 0, 32, s[0:1]
	v_ldexp_f32 v98, v98, v100
	v_log_f32_e32 v98, v98
	s_nop 0
	v_mul_f32_e32 v100, 0x3f317217, v98
	v_fma_f32 v100, v98, s8, -v100
	v_fmac_f32_e32 v100, 0x3377d1cf, v98
	v_fmac_f32_e32 v100, 0x3f317217, v98
	v_cmp_lt_f32_e64 s[4:5], |v98|, s9
	s_nop 1
	v_cndmask_b32_e64 v98, v98, v100, s[4:5]
	v_cndmask_b32_e64 v100, 0, v226, s[0:1]
	v_sub_f32_e32 v98, v98, v100
	v_add_f32_e32 v98, v99, v98
	v_mov_b32_e32 v99, s69
	ds_read_b128 v[184:187], v99 offset:4096
	ds_read_b128 v[188:191], v99 offset:4112
	ds_read_b128 v[192:195], v99 offset:4128
	ds_read_b128 v[196:199], v99 offset:4144
	s_nop 0
	s_nop 0
	s_nop 0
	s_nop 0
	v_mul_f32_e32 v98, 0xbd800000, v98
	s_nop 0
	s_waitcnt lgkmcnt(3)
	v_mul_f32_e32 v99, v6, v185
	v_fmac_f32_e32 v99, v4, v184
	s_waitcnt lgkmcnt(2)
	v_mul_f32_e32 v100, v7, v189
	v_fmac_f32_e32 v99, v8, v186
	v_fmac_f32_e32 v100, v5, v188
	v_fmac_f32_e32 v99, v10, v187
	v_fmac_f32_e32 v100, v9, v190
	v_add_f32_e32 v99, v26, v99
	v_fmac_f32_e32 v100, v11, v191
	v_add_f32_e32 v99, v99, v100
	s_waitcnt lgkmcnt(1)
	v_mul_f32_e32 v100, v14, v193
	v_fmac_f32_e32 v100, v12, v192
	v_fmac_f32_e32 v100, v16, v194
	v_fmac_f32_e32 v100, v18, v195
	v_add_f32_e32 v99, v99, v100
	s_waitcnt lgkmcnt(0)
	v_mul_f32_e32 v100, v15, v197
	v_fmac_f32_e32 v100, v13, v196
	v_fmac_f32_e32 v100, v17, v198
	v_fmac_f32_e32 v100, v19, v199
	v_add_f32_e32 v99, v99, v100
	v_max_f32_e64 v100, -v99, 0
	v_mul_f32_e64 v99, |v99|, s6
	v_exp_f32_e32 v99, v99
	v_cndmask_b32_e64 v98, 0, v98, s[58:59]
	v_add_f32_e32 v1, v1, v98
	v_add_f32_e32 v99, 1.0, v99
	v_cmp_gt_f32_e64 s[0:1], s7, v99
	s_nop 1
	v_cndmask_b32_e64 v101, 0, 32, s[0:1]
	v_ldexp_f32 v99, v99, v101
	v_log_f32_e32 v99, v99
	s_nop 0
	v_mul_f32_e32 v101, 0x3f317217, v99
	v_fma_f32 v101, v99, s8, -v101
	v_fmac_f32_e32 v101, 0x3377d1cf, v99
	v_fmac_f32_e32 v101, 0x3f317217, v99
	v_cmp_lt_f32_e64 s[4:5], |v99|, s9
	s_nop 1
	v_cndmask_b32_e64 v99, v99, v101, s[4:5]
	v_cndmask_b32_e64 v101, 0, v226, s[0:1]
	v_readlane_b32 s0, v255, 13
	v_sub_f32_e32 v99, v99, v101
	v_add_f32_e32 v99, v100, v99
	v_mov_b32_e32 v112, s0
	ds_read_b128 v[184:187], v112 offset:4096
	ds_read_b128 v[188:191], v112 offset:4112
	ds_read_b128 v[192:195], v112 offset:4128
	ds_read_b128 v[196:199], v112 offset:4144
	s_nop 0
	s_nop 0
	s_nop 0
	s_nop 0
	v_mul_f32_e32 v99, 0xbd800000, v99
	s_nop 0
	s_waitcnt lgkmcnt(3)
	v_mul_f32_e32 v101, v6, v185
	v_fmac_f32_e32 v101, v4, v184
	v_fmac_f32_e32 v101, v8, v186
	v_fmac_f32_e32 v101, v10, v187
	v_add_f32_e32 v100, v26, v101
	s_waitcnt lgkmcnt(2)
	v_mul_f32_e32 v101, v7, v189
	v_fmac_f32_e32 v101, v5, v188
	v_fmac_f32_e32 v101, v9, v190
	v_fmac_f32_e32 v101, v11, v191
	v_add_f32_e32 v100, v100, v101
	s_waitcnt lgkmcnt(1)
	v_mul_f32_e32 v101, v14, v193
	v_fmac_f32_e32 v101, v12, v192
	v_fmac_f32_e32 v101, v16, v194
	v_fmac_f32_e32 v101, v18, v195
	v_add_f32_e32 v100, v100, v101
	s_waitcnt lgkmcnt(0)
	v_mul_f32_e32 v101, v15, v197
	v_fmac_f32_e32 v101, v13, v196
	v_fmac_f32_e32 v101, v17, v198
	v_fmac_f32_e32 v101, v19, v199
	v_add_f32_e32 v100, v100, v101
	v_max_f32_e64 v101, -v100, 0
	v_mul_f32_e64 v100, |v100|, s6
	v_exp_f32_e32 v100, v100
	v_cndmask_b32_e64 v99, 0, v99, s[56:57]
	v_add_f32_e32 v1, v1, v99
	v_add_f32_e32 v100, 1.0, v100
	v_cmp_gt_f32_e64 s[0:1], s7, v100
	s_nop 1
	v_cndmask_b32_e64 v102, 0, 32, s[0:1]
	v_ldexp_f32 v100, v100, v102
	v_log_f32_e32 v100, v100
	s_nop 0
	v_mul_f32_e32 v102, 0x3f317217, v100
	v_fma_f32 v102, v100, s8, -v102
	v_fmac_f32_e32 v102, 0x3377d1cf, v100
	v_fmac_f32_e32 v102, 0x3f317217, v100
	v_cmp_lt_f32_e64 s[4:5], |v100|, s9
	s_nop 1
	v_cndmask_b32_e64 v100, v100, v102, s[4:5]
	v_cndmask_b32_e64 v102, 0, v226, s[0:1]
	v_sub_f32_e32 v100, v100, v102
	v_readlane_b32 s0, v255, 9
	v_add_f32_e32 v100, v101, v100
	v_mul_f32_e32 v100, 0xbd800000, v100
	v_mov_b32_e32 v101, s0
	ds_read_b128 v[184:187], v101 offset:4096
	ds_read_b128 v[188:191], v101 offset:4112
	ds_read_b128 v[192:195], v101 offset:4128
	ds_read_b128 v[196:199], v101 offset:4144
	s_nop 0
	s_nop 0
	s_nop 0
	s_nop 0
	v_cndmask_b32_e64 v100, 0, v100, s[54:55]
	s_nop 0
	s_waitcnt lgkmcnt(3)
	v_mul_f32_e32 v101, v6, v185
	v_fmac_f32_e32 v101, v4, v184
	s_waitcnt lgkmcnt(2)
	v_mul_f32_e32 v102, v7, v189
	v_fmac_f32_e32 v101, v8, v186
	v_fmac_f32_e32 v102, v5, v188
	v_fmac_f32_e32 v101, v10, v187
	v_fmac_f32_e32 v102, v9, v190
	v_add_f32_e32 v101, v26, v101
	v_fmac_f32_e32 v102, v11, v191
	v_add_f32_e32 v101, v101, v102
	s_waitcnt lgkmcnt(1)
	v_mul_f32_e32 v102, v14, v193
	v_fmac_f32_e32 v102, v12, v192
	v_fmac_f32_e32 v102, v16, v194
	v_fmac_f32_e32 v102, v18, v195
	v_add_f32_e32 v101, v101, v102
	s_waitcnt lgkmcnt(0)
	v_mul_f32_e32 v102, v15, v197
	v_fmac_f32_e32 v102, v13, v196
	v_fmac_f32_e32 v102, v17, v198
	v_fmac_f32_e32 v102, v19, v199
	v_add_f32_e32 v101, v101, v102
	v_max_f32_e64 v102, -v101, 0
	v_mul_f32_e64 v101, |v101|, s6
	v_exp_f32_e32 v101, v101
	v_add_f32_e32 v1, v1, v100
	v_add_f32_e32 v101, 1.0, v101
	v_cmp_gt_f32_e64 s[0:1], s7, v101
	s_nop 1
	v_cndmask_b32_e64 v103, 0, 32, s[0:1]
	v_ldexp_f32 v101, v101, v103
	v_log_f32_e32 v101, v101
	s_nop 0
	v_mul_f32_e32 v103, 0x3f317217, v101
	v_fma_f32 v103, v101, s8, -v103
	v_fmac_f32_e32 v103, 0x3377d1cf, v101
	v_fmac_f32_e32 v103, 0x3f317217, v101
	v_cmp_lt_f32_e64 s[4:5], |v101|, s9
	s_nop 1
	v_cndmask_b32_e64 v101, v101, v103, s[4:5]
	v_cndmask_b32_e64 v103, 0, v226, s[0:1]
	v_readlane_b32 s0, v254, 49
	v_sub_f32_e32 v101, v101, v103
	v_add_f32_e32 v101, v102, v101
	v_mov_b32_e32 v114, s0
	ds_read_b128 v[184:187], v114 offset:4096
	ds_read_b128 v[188:191], v114 offset:4112
	ds_read_b128 v[192:195], v114 offset:4128
	ds_read_b128 v[196:199], v114 offset:4144
	s_nop 0
	s_nop 0
	s_nop 0
	s_nop 0
	v_mul_f32_e32 v101, 0xbd800000, v101
	s_nop 0
	s_waitcnt lgkmcnt(3)
	v_mul_f32_e32 v103, v6, v185
	v_fmac_f32_e32 v103, v4, v184
	v_fmac_f32_e32 v103, v8, v186
	v_fmac_f32_e32 v103, v10, v187
	v_add_f32_e32 v102, v26, v103
	s_waitcnt lgkmcnt(2)
	v_mul_f32_e32 v103, v7, v189
	v_fmac_f32_e32 v103, v5, v188
	v_fmac_f32_e32 v103, v9, v190
	v_fmac_f32_e32 v103, v11, v191
	v_add_f32_e32 v102, v102, v103
	s_waitcnt lgkmcnt(1)
	v_mul_f32_e32 v103, v14, v193
	v_fmac_f32_e32 v103, v12, v192
	v_fmac_f32_e32 v103, v16, v194
	v_fmac_f32_e32 v103, v18, v195
	v_add_f32_e32 v102, v102, v103
	s_waitcnt lgkmcnt(0)
	v_mul_f32_e32 v103, v15, v197
	v_fmac_f32_e32 v103, v13, v196
	v_fmac_f32_e32 v103, v17, v198
	v_fmac_f32_e32 v103, v19, v199
	v_add_f32_e32 v102, v102, v103
	v_max_f32_e64 v103, -v102, 0
	v_mul_f32_e64 v102, |v102|, s6
	v_exp_f32_e32 v102, v102
	v_cndmask_b32_e64 v101, 0, v101, s[52:53]
	v_add_f32_e32 v1, v1, v101
	v_add_f32_e32 v102, 1.0, v102
	v_cmp_gt_f32_e64 s[0:1], s7, v102
	s_nop 1
	v_cndmask_b32_e64 v104, 0, 32, s[0:1]
	v_ldexp_f32 v102, v102, v104
	v_log_f32_e32 v102, v102
	s_nop 0
	v_mul_f32_e32 v104, 0x3f317217, v102
	v_fma_f32 v104, v102, s8, -v104
	v_fmac_f32_e32 v104, 0x3377d1cf, v102
	v_fmac_f32_e32 v104, 0x3f317217, v102
	v_cmp_lt_f32_e64 s[4:5], |v102|, s9
	s_nop 1
	v_cndmask_b32_e64 v102, v102, v104, s[4:5]
	v_cndmask_b32_e64 v104, 0, v226, s[0:1]
	v_sub_f32_e32 v102, v102, v104
	v_readlane_b32 s0, v254, 52
	v_add_f32_e32 v102, v103, v102
	v_mul_f32_e32 v102, 0xbd800000, v102
	v_mov_b32_e32 v103, s0
	ds_read_b128 v[184:187], v103 offset:4096
	ds_read_b128 v[188:191], v103 offset:4112
	ds_read_b128 v[192:195], v103 offset:4128
	ds_read_b128 v[196:199], v103 offset:4144
	s_nop 0
	s_nop 0
	s_nop 0
	s_nop 0
	v_cndmask_b32_e64 v102, 0, v102, s[48:49]
	s_nop 0
	s_waitcnt lgkmcnt(3)
	v_mul_f32_e32 v103, v6, v185
	v_fmac_f32_e32 v103, v4, v184
	s_waitcnt lgkmcnt(2)
	v_mul_f32_e32 v104, v7, v189
	v_fmac_f32_e32 v103, v8, v186
	v_fmac_f32_e32 v104, v5, v188
	v_fmac_f32_e32 v103, v10, v187
	v_fmac_f32_e32 v104, v9, v190
	v_add_f32_e32 v103, v26, v103
	v_fmac_f32_e32 v104, v11, v191
	v_add_f32_e32 v103, v103, v104
	s_waitcnt lgkmcnt(1)
	v_mul_f32_e32 v104, v14, v193
	v_fmac_f32_e32 v104, v12, v192
	v_fmac_f32_e32 v104, v16, v194
	v_fmac_f32_e32 v104, v18, v195
	v_add_f32_e32 v103, v103, v104
	s_waitcnt lgkmcnt(0)
	v_mul_f32_e32 v104, v15, v197
	v_fmac_f32_e32 v104, v13, v196
	v_fmac_f32_e32 v104, v17, v198
	v_fmac_f32_e32 v104, v19, v199
	v_add_f32_e32 v103, v103, v104
	v_max_f32_e64 v104, -v103, 0
	v_mul_f32_e64 v103, |v103|, s6
	v_exp_f32_e32 v103, v103
	v_add_f32_e32 v1, v1, v102
	v_add_f32_e32 v103, 1.0, v103
	v_cmp_gt_f32_e64 s[0:1], s7, v103
	s_nop 1
	v_cndmask_b32_e64 v105, 0, 32, s[0:1]
	v_ldexp_f32 v103, v103, v105
	v_log_f32_e32 v103, v103
	s_nop 0
	v_mul_f32_e32 v105, 0x3f317217, v103
	v_fma_f32 v105, v103, s8, -v105
	v_fmac_f32_e32 v105, 0x3377d1cf, v103
	v_fmac_f32_e32 v105, 0x3f317217, v103
	v_cmp_lt_f32_e64 s[4:5], |v103|, s9
	s_nop 1
	v_cndmask_b32_e64 v103, v103, v105, s[4:5]
	v_cndmask_b32_e64 v105, 0, v226, s[0:1]
	v_readlane_b32 s0, v254, 55
	v_sub_f32_e32 v103, v103, v105
	v_add_f32_e32 v103, v104, v103
	v_mov_b32_e32 v116, s0
	ds_read_b128 v[184:187], v116 offset:4096
	ds_read_b128 v[188:191], v116 offset:4112
	ds_read_b128 v[192:195], v116 offset:4128
	ds_read_b128 v[196:199], v116 offset:4144
	s_nop 0
	s_nop 0
	s_nop 0
	s_nop 0
	v_mul_f32_e32 v103, 0xbd800000, v103
	s_nop 0
	s_waitcnt lgkmcnt(3)
	v_mul_f32_e32 v105, v6, v185
	v_fmac_f32_e32 v105, v4, v184
	v_fmac_f32_e32 v105, v8, v186
	v_fmac_f32_e32 v105, v10, v187
	v_add_f32_e32 v104, v26, v105
	s_waitcnt lgkmcnt(2)
	v_mul_f32_e32 v105, v7, v189
	v_fmac_f32_e32 v105, v5, v188
	v_fmac_f32_e32 v105, v9, v190
	v_fmac_f32_e32 v105, v11, v191
	v_add_f32_e32 v104, v104, v105
	s_waitcnt lgkmcnt(1)
	v_mul_f32_e32 v105, v14, v193
	v_fmac_f32_e32 v105, v12, v192
	v_fmac_f32_e32 v105, v16, v194
	v_fmac_f32_e32 v105, v18, v195
	v_add_f32_e32 v104, v104, v105
	s_waitcnt lgkmcnt(0)
	v_mul_f32_e32 v105, v15, v197
	v_fmac_f32_e32 v105, v13, v196
	v_fmac_f32_e32 v105, v17, v198
	v_fmac_f32_e32 v105, v19, v199
	v_add_f32_e32 v104, v104, v105
	v_max_f32_e64 v105, -v104, 0
	v_mul_f32_e64 v104, |v104|, s6
	v_exp_f32_e32 v104, v104
	v_cndmask_b32_e64 v103, 0, v103, s[46:47]
	v_add_f32_e32 v1, v1, v103
	v_add_f32_e32 v104, 1.0, v104
	v_cmp_gt_f32_e64 s[0:1], s7, v104
	s_nop 1
	v_cndmask_b32_e64 v106, 0, 32, s[0:1]
	v_ldexp_f32 v104, v104, v106
	v_log_f32_e32 v104, v104
	s_nop 0
	v_mul_f32_e32 v106, 0x3f317217, v104
	v_fma_f32 v106, v104, s8, -v106
	v_fmac_f32_e32 v106, 0x3377d1cf, v104
	v_fmac_f32_e32 v106, 0x3f317217, v104
	v_cmp_lt_f32_e64 s[4:5], |v104|, s9
	s_nop 1
	v_cndmask_b32_e64 v104, v104, v106, s[4:5]
	v_cndmask_b32_e64 v106, 0, v226, s[0:1]
	v_sub_f32_e32 v104, v104, v106
	v_readlane_b32 s0, v254, 58
	v_add_f32_e32 v104, v105, v104
	v_mul_f32_e32 v104, 0xbd800000, v104
	v_mov_b32_e32 v105, s0
	ds_read_b128 v[184:187], v105 offset:4096
	ds_read_b128 v[188:191], v105 offset:4112
	ds_read_b128 v[192:195], v105 offset:4128
	ds_read_b128 v[196:199], v105 offset:4144
	s_nop 0
	s_nop 0
	s_nop 0
	s_nop 0
	v_cndmask_b32_e64 v104, 0, v104, s[42:43]
	s_nop 0
	s_waitcnt lgkmcnt(3)
	v_mul_f32_e32 v105, v6, v185
	v_fmac_f32_e32 v105, v4, v184
	s_waitcnt lgkmcnt(2)
	v_mul_f32_e32 v106, v7, v189
	v_fmac_f32_e32 v105, v8, v186
	v_fmac_f32_e32 v106, v5, v188
	v_fmac_f32_e32 v105, v10, v187
	v_fmac_f32_e32 v106, v9, v190
	v_add_f32_e32 v105, v26, v105
	v_fmac_f32_e32 v106, v11, v191
	v_add_f32_e32 v105, v105, v106
	s_waitcnt lgkmcnt(1)
	v_mul_f32_e32 v106, v14, v193
	v_fmac_f32_e32 v106, v12, v192
	v_fmac_f32_e32 v106, v16, v194
	v_fmac_f32_e32 v106, v18, v195
	v_add_f32_e32 v105, v105, v106
	s_waitcnt lgkmcnt(0)
	v_mul_f32_e32 v106, v15, v197
	v_fmac_f32_e32 v106, v13, v196
	v_fmac_f32_e32 v106, v17, v198
	v_fmac_f32_e32 v106, v19, v199
	v_add_f32_e32 v105, v105, v106
	v_max_f32_e64 v106, -v105, 0
	v_mul_f32_e64 v105, |v105|, s6
	v_exp_f32_e32 v105, v105
	v_add_f32_e32 v1, v1, v104
	v_add_f32_e32 v105, 1.0, v105
	v_cmp_gt_f32_e64 s[0:1], s7, v105
	s_nop 1
	v_cndmask_b32_e64 v107, 0, 32, s[0:1]
	v_ldexp_f32 v105, v105, v107
	v_log_f32_e32 v105, v105
	s_nop 0
	v_mul_f32_e32 v107, 0x3f317217, v105
	v_fma_f32 v107, v105, s8, -v107
	v_fmac_f32_e32 v107, 0x3377d1cf, v105
	v_fmac_f32_e32 v107, 0x3f317217, v105
	v_cmp_lt_f32_e64 s[4:5], |v105|, s9
	s_nop 1
	v_cndmask_b32_e64 v105, v105, v107, s[4:5]
	v_cndmask_b32_e64 v107, 0, v226, s[0:1]
	v_readlane_b32 s0, v254, 61
	v_sub_f32_e32 v105, v105, v107
	v_add_f32_e32 v105, v106, v105
	v_mov_b32_e32 v118, s0
	ds_read_b128 v[184:187], v118 offset:4096
	ds_read_b128 v[188:191], v118 offset:4112
	ds_read_b128 v[192:195], v118 offset:4128
	ds_read_b128 v[196:199], v118 offset:4144
	s_nop 0
	s_nop 0
	s_nop 0
	s_nop 0
	v_mul_f32_e32 v105, 0xbd800000, v105
	s_nop 0
	s_waitcnt lgkmcnt(3)
	v_mul_f32_e32 v107, v6, v185
	v_fmac_f32_e32 v107, v4, v184
	v_fmac_f32_e32 v107, v8, v186
	v_fmac_f32_e32 v107, v10, v187
	v_add_f32_e32 v106, v26, v107
	s_waitcnt lgkmcnt(2)
	v_mul_f32_e32 v107, v7, v189
	v_fmac_f32_e32 v107, v5, v188
	v_fmac_f32_e32 v107, v9, v190
	v_fmac_f32_e32 v107, v11, v191
	v_add_f32_e32 v106, v106, v107
	s_waitcnt lgkmcnt(1)
	v_mul_f32_e32 v107, v14, v193
	v_fmac_f32_e32 v107, v12, v192
	v_fmac_f32_e32 v107, v16, v194
	v_fmac_f32_e32 v107, v18, v195
	v_add_f32_e32 v106, v106, v107
	s_waitcnt lgkmcnt(0)
	v_mul_f32_e32 v107, v15, v197
	v_fmac_f32_e32 v107, v13, v196
	v_fmac_f32_e32 v107, v17, v198
	v_fmac_f32_e32 v107, v19, v199
	v_add_f32_e32 v106, v106, v107
	v_max_f32_e64 v107, -v106, 0
	v_mul_f32_e64 v106, |v106|, s6
	v_exp_f32_e32 v106, v106
	v_cndmask_b32_e64 v105, 0, v105, s[14:15]
	v_add_f32_e32 v1, v1, v105
	v_add_f32_e32 v106, 1.0, v106
	v_cmp_gt_f32_e64 s[0:1], s7, v106
	s_nop 1
	v_cndmask_b32_e64 v108, 0, 32, s[0:1]
	v_ldexp_f32 v106, v106, v108
	v_log_f32_e32 v106, v106
	s_nop 0
	v_mul_f32_e32 v108, 0x3f317217, v106
	v_fma_f32 v108, v106, s8, -v108
	v_fmac_f32_e32 v108, 0x3377d1cf, v106
	v_fmac_f32_e32 v108, 0x3f317217, v106
	v_cmp_lt_f32_e64 s[4:5], |v106|, s9
	s_nop 1
	v_cndmask_b32_e64 v106, v106, v108, s[4:5]
	v_cndmask_b32_e64 v108, 0, v226, s[0:1]
	v_sub_f32_e32 v106, v106, v108
	v_readlane_b32 s0, v253, 0
	v_add_f32_e32 v106, v107, v106
	v_mul_f32_e32 v106, 0xbd800000, v106
	v_mov_b32_e32 v107, s0
	ds_read_b128 v[184:187], v107 offset:4096
	ds_read_b128 v[188:191], v107 offset:4112
	ds_read_b128 v[192:195], v107 offset:4128
	ds_read_b128 v[196:199], v107 offset:4144
	s_nop 0
	s_nop 0
	s_nop 0
	s_nop 0
	v_cndmask_b32_e64 v106, 0, v106, s[40:41]
	s_nop 0
	s_waitcnt lgkmcnt(3)
	v_mul_f32_e32 v107, v6, v185
	v_fmac_f32_e32 v107, v4, v184
	s_waitcnt lgkmcnt(2)
	v_mul_f32_e32 v108, v7, v189
	v_fmac_f32_e32 v107, v8, v186
	v_fmac_f32_e32 v108, v5, v188
	v_fmac_f32_e32 v107, v10, v187
	v_fmac_f32_e32 v108, v9, v190
	v_add_f32_e32 v107, v26, v107
	v_fmac_f32_e32 v108, v11, v191
	v_add_f32_e32 v107, v107, v108
	s_waitcnt lgkmcnt(1)
	v_mul_f32_e32 v108, v14, v193
	v_fmac_f32_e32 v108, v12, v192
	v_fmac_f32_e32 v108, v16, v194
	v_fmac_f32_e32 v108, v18, v195
	v_add_f32_e32 v107, v107, v108
	s_waitcnt lgkmcnt(0)
	v_mul_f32_e32 v108, v15, v197
	v_fmac_f32_e32 v108, v13, v196
	v_fmac_f32_e32 v108, v17, v198
	v_fmac_f32_e32 v108, v19, v199
	v_add_f32_e32 v107, v107, v108
	v_max_f32_e64 v108, -v107, 0
	v_mul_f32_e64 v107, |v107|, s6
	v_exp_f32_e32 v107, v107
	v_add_f32_e32 v1, v1, v106
	v_add_f32_e32 v107, 1.0, v107
	v_cmp_gt_f32_e64 s[0:1], s7, v107
	s_nop 1
	v_cndmask_b32_e64 v109, 0, 32, s[0:1]
	v_ldexp_f32 v107, v107, v109
	v_log_f32_e32 v107, v107
	s_nop 0
	v_mul_f32_e32 v109, 0x3f317217, v107
	v_fma_f32 v109, v107, s8, -v109
	v_fmac_f32_e32 v109, 0x3377d1cf, v107
	v_fmac_f32_e32 v109, 0x3f317217, v107
	v_cmp_lt_f32_e64 s[4:5], |v107|, s9
	s_nop 1
	v_cndmask_b32_e64 v107, v107, v109, s[4:5]
	v_cndmask_b32_e64 v109, 0, v226, s[0:1]
	v_readlane_b32 s0, v253, 3
	v_sub_f32_e32 v107, v107, v109
	v_add_f32_e32 v107, v108, v107
	v_mov_b32_e32 v120, s0
	ds_read_b128 v[184:187], v120 offset:4096
	ds_read_b128 v[188:191], v120 offset:4112
	ds_read_b128 v[192:195], v120 offset:4128
	ds_read_b128 v[196:199], v120 offset:4144
	s_nop 0
	s_nop 0
	s_nop 0
	s_nop 0
	v_mul_f32_e32 v107, 0xbd800000, v107
	s_nop 0
	s_waitcnt lgkmcnt(3)
	v_mul_f32_e32 v109, v6, v185
	v_fmac_f32_e32 v109, v4, v184
	v_fmac_f32_e32 v109, v8, v186
	v_fmac_f32_e32 v109, v10, v187
	v_add_f32_e32 v108, v26, v109
	s_waitcnt lgkmcnt(2)
	v_mul_f32_e32 v109, v7, v189
	v_fmac_f32_e32 v109, v5, v188
	v_fmac_f32_e32 v109, v9, v190
	v_fmac_f32_e32 v109, v11, v191
	v_add_f32_e32 v108, v108, v109
	s_waitcnt lgkmcnt(1)
	v_mul_f32_e32 v109, v14, v193
	v_fmac_f32_e32 v109, v12, v192
	v_fmac_f32_e32 v109, v16, v194
	v_fmac_f32_e32 v109, v18, v195
	v_add_f32_e32 v108, v108, v109
	s_waitcnt lgkmcnt(0)
	v_mul_f32_e32 v109, v15, v197
	v_fmac_f32_e32 v109, v13, v196
	v_fmac_f32_e32 v109, v17, v198
	v_fmac_f32_e32 v109, v19, v199
	v_add_f32_e32 v108, v108, v109
	v_max_f32_e64 v109, -v108, 0
	v_mul_f32_e64 v108, |v108|, s6
	v_exp_f32_e32 v108, v108
	v_cndmask_b32_e64 v107, 0, v107, s[36:37]
	v_add_f32_e32 v1, v1, v107
	v_add_f32_e32 v108, 1.0, v108
	v_cmp_gt_f32_e64 s[0:1], s7, v108
	s_nop 1
	v_cndmask_b32_e64 v110, 0, 32, s[0:1]
	v_ldexp_f32 v108, v108, v110
	v_log_f32_e32 v108, v108
	s_nop 0
	v_mul_f32_e32 v110, 0x3f317217, v108
	v_fma_f32 v110, v108, s8, -v110
	v_fmac_f32_e32 v110, 0x3377d1cf, v108
	v_fmac_f32_e32 v110, 0x3f317217, v108
	v_cmp_lt_f32_e64 s[4:5], |v108|, s9
	s_nop 1
	v_cndmask_b32_e64 v108, v108, v110, s[4:5]
	v_cndmask_b32_e64 v110, 0, v226, s[0:1]
	v_sub_f32_e32 v108, v108, v110
	v_readlane_b32 s0, v253, 6
	v_add_f32_e32 v108, v109, v108
	v_mul_f32_e32 v108, 0xbd800000, v108
	v_mov_b32_e32 v109, s0
	ds_read_b128 v[184:187], v109 offset:4096
	ds_read_b128 v[188:191], v109 offset:4112
	ds_read_b128 v[192:195], v109 offset:4128
	ds_read_b128 v[196:199], v109 offset:4144
	s_nop 0
	s_nop 0
	s_nop 0
	s_nop 0
	v_cndmask_b32_e64 v108, 0, v108, s[34:35]
	s_nop 0
	s_waitcnt lgkmcnt(3)
	v_mul_f32_e32 v109, v6, v185
	v_fmac_f32_e32 v109, v4, v184
	s_waitcnt lgkmcnt(2)
	v_mul_f32_e32 v110, v7, v189
	v_fmac_f32_e32 v109, v8, v186
	v_fmac_f32_e32 v110, v5, v188
	v_fmac_f32_e32 v109, v10, v187
	v_fmac_f32_e32 v110, v9, v190
	v_add_f32_e32 v109, v26, v109
	v_fmac_f32_e32 v110, v11, v191
	v_add_f32_e32 v109, v109, v110
	s_waitcnt lgkmcnt(1)
	v_mul_f32_e32 v110, v14, v193
	v_fmac_f32_e32 v110, v12, v192
	v_fmac_f32_e32 v110, v16, v194
	v_fmac_f32_e32 v110, v18, v195
	v_add_f32_e32 v109, v109, v110
	s_waitcnt lgkmcnt(0)
	v_mul_f32_e32 v110, v15, v197
	v_fmac_f32_e32 v110, v13, v196
	v_fmac_f32_e32 v110, v17, v198
	v_fmac_f32_e32 v110, v19, v199
	v_add_f32_e32 v109, v109, v110
	v_max_f32_e64 v110, -v109, 0
	v_mul_f32_e64 v109, |v109|, s6
	v_exp_f32_e32 v109, v109
	v_mov_b32_e32 v122, s97
	ds_read_b128 v[184:187], v122 offset:4096
	ds_read_b128 v[188:191], v122 offset:4112
	ds_read_b128 v[192:195], v122 offset:4128
	ds_read_b128 v[196:199], v122 offset:4144
	v_add_f32_e32 v1, v1, v108
	v_add_f32_e32 v109, 1.0, v109
	v_cmp_gt_f32_e64 s[0:1], s7, v109
	s_nop 1
	v_cndmask_b32_e64 v111, 0, 32, s[0:1]
	v_ldexp_f32 v109, v109, v111
	v_log_f32_e32 v109, v109
	s_nop 0
	v_mul_f32_e32 v111, 0x3f317217, v109
	v_fma_f32 v111, v109, s8, -v111
	v_fmac_f32_e32 v111, 0x3377d1cf, v109
	v_fmac_f32_e32 v111, 0x3f317217, v109
	v_cmp_lt_f32_e64 s[4:5], |v109|, s9
	s_nop 1
	v_cndmask_b32_e64 v109, v109, v111, s[4:5]
	v_cndmask_b32_e64 v111, 0, v226, s[0:1]
	v_sub_f32_e32 v109, v109, v111
	v_add_f32_e32 v109, v110, v109
	s_nop 0
	s_nop 0
	s_nop 0
	s_nop 0
	v_mul_f32_e32 v109, 0xbd800000, v109
	s_nop 0
	s_waitcnt lgkmcnt(3)
	v_mul_f32_e32 v111, v6, v185
	v_fmac_f32_e32 v111, v4, v184
	v_fmac_f32_e32 v111, v8, v186
	v_fmac_f32_e32 v111, v10, v187
	v_add_f32_e32 v110, v26, v111
	s_waitcnt lgkmcnt(2)
	v_mul_f32_e32 v111, v7, v189
	v_fmac_f32_e32 v111, v5, v188
	v_fmac_f32_e32 v111, v9, v190
	v_fmac_f32_e32 v111, v11, v191
	v_add_f32_e32 v110, v110, v111
	s_waitcnt lgkmcnt(1)
	v_mul_f32_e32 v111, v14, v193
	v_fmac_f32_e32 v111, v12, v192
	v_fmac_f32_e32 v111, v16, v194
	v_fmac_f32_e32 v111, v18, v195
	v_add_f32_e32 v110, v110, v111
	s_waitcnt lgkmcnt(0)
	v_mul_f32_e32 v111, v15, v197
	v_fmac_f32_e32 v111, v13, v196
	v_fmac_f32_e32 v111, v17, v198
	v_fmac_f32_e32 v111, v19, v199
	v_add_f32_e32 v110, v110, v111
	v_max_f32_e64 v111, -v110, 0
	v_mul_f32_e64 v110, |v110|, s6
	v_exp_f32_e32 v110, v110
	v_cndmask_b32_e64 v109, 0, v109, s[30:31]
	v_add_f32_e32 v1, v1, v109
	v_add_f32_e32 v110, 1.0, v110
	v_cmp_gt_f32_e64 s[0:1], s7, v110
	s_nop 1
	v_cndmask_b32_e64 v112, 0, 32, s[0:1]
	v_ldexp_f32 v110, v110, v112
	v_log_f32_e32 v110, v110
	s_nop 0
	v_mul_f32_e32 v112, 0x3f317217, v110
	v_fma_f32 v112, v110, s8, -v112
	v_fmac_f32_e32 v112, 0x3377d1cf, v110
	v_fmac_f32_e32 v112, 0x3f317217, v110
	v_cmp_lt_f32_e64 s[4:5], |v110|, s9
	s_nop 1
	v_cndmask_b32_e64 v110, v110, v112, s[4:5]
	v_cndmask_b32_e64 v112, 0, v226, s[0:1]
	v_sub_f32_e32 v110, v110, v112
	v_add_f32_e32 v110, v111, v110
	v_mov_b32_e32 v111, s95
	ds_read_b128 v[184:187], v111 offset:4096
	ds_read_b128 v[188:191], v111 offset:4112
	ds_read_b128 v[192:195], v111 offset:4128
	ds_read_b128 v[196:199], v111 offset:4144
	s_nop 0
	s_nop 0
	s_nop 0
	s_nop 0
	v_mul_f32_e32 v110, 0xbd800000, v110
	s_nop 0
	s_waitcnt lgkmcnt(3)
	v_mul_f32_e32 v111, v6, v185
	v_fmac_f32_e32 v111, v4, v184
	s_waitcnt lgkmcnt(2)
	v_mul_f32_e32 v112, v7, v189
	v_fmac_f32_e32 v111, v8, v186
	v_fmac_f32_e32 v112, v5, v188
	v_fmac_f32_e32 v111, v10, v187
	v_fmac_f32_e32 v112, v9, v190
	v_add_f32_e32 v111, v26, v111
	v_fmac_f32_e32 v112, v11, v191
	v_add_f32_e32 v111, v111, v112
	s_waitcnt lgkmcnt(1)
	v_mul_f32_e32 v112, v14, v193
	v_fmac_f32_e32 v112, v12, v192
	v_fmac_f32_e32 v112, v16, v194
	v_fmac_f32_e32 v112, v18, v195
	v_add_f32_e32 v111, v111, v112
	s_waitcnt lgkmcnt(0)
	v_mul_f32_e32 v112, v15, v197
	v_fmac_f32_e32 v112, v13, v196
	v_fmac_f32_e32 v112, v17, v198
	v_fmac_f32_e32 v112, v19, v199
	v_add_f32_e32 v111, v111, v112
	v_max_f32_e64 v112, -v111, 0
	v_mul_f32_e64 v111, |v111|, s6
	v_exp_f32_e32 v111, v111
	v_mov_b32_e32 v124, s94
	ds_read_b128 v[184:187], v124 offset:4096
	ds_read_b128 v[188:191], v124 offset:4112
	ds_read_b128 v[192:195], v124 offset:4128
	ds_read_b128 v[196:199], v124 offset:4144
	v_cndmask_b32_e64 v110, 0, v110, s[24:25]
	v_add_f32_e32 v1, v1, v110
	v_add_f32_e32 v111, 1.0, v111
	v_cmp_gt_f32_e64 s[0:1], s7, v111
	s_nop 1
	v_cndmask_b32_e64 v113, 0, 32, s[0:1]
	v_ldexp_f32 v111, v111, v113
	v_log_f32_e32 v111, v111
	s_nop 0
	v_mul_f32_e32 v113, 0x3f317217, v111
	v_fma_f32 v113, v111, s8, -v113
	v_fmac_f32_e32 v113, 0x3377d1cf, v111
	v_fmac_f32_e32 v113, 0x3f317217, v111
	v_cmp_lt_f32_e64 s[4:5], |v111|, s9
	s_nop 1
	v_cndmask_b32_e64 v111, v111, v113, s[4:5]
	v_cndmask_b32_e64 v113, 0, v226, s[0:1]
	v_sub_f32_e32 v111, v111, v113
	v_add_f32_e32 v111, v112, v111
	s_nop 0
	s_nop 0
	s_nop 0
	s_nop 0
	v_mul_f32_e32 v111, 0xbd800000, v111
	s_nop 0
	s_waitcnt lgkmcnt(3)
	v_mul_f32_e32 v113, v6, v185
	v_fmac_f32_e32 v113, v4, v184
	v_fmac_f32_e32 v113, v8, v186
	v_fmac_f32_e32 v113, v10, v187
	v_add_f32_e32 v112, v26, v113
	s_waitcnt lgkmcnt(2)
	v_mul_f32_e32 v113, v7, v189
	v_fmac_f32_e32 v113, v5, v188
	v_fmac_f32_e32 v113, v9, v190
	v_fmac_f32_e32 v113, v11, v191
	v_add_f32_e32 v112, v112, v113
	s_waitcnt lgkmcnt(1)
	v_mul_f32_e32 v113, v14, v193
	v_fmac_f32_e32 v113, v12, v192
	v_fmac_f32_e32 v113, v16, v194
	v_fmac_f32_e32 v113, v18, v195
	v_add_f32_e32 v112, v112, v113
	s_waitcnt lgkmcnt(0)
	v_mul_f32_e32 v113, v15, v197
	v_fmac_f32_e32 v113, v13, v196
	v_fmac_f32_e32 v113, v17, v198
	v_fmac_f32_e32 v113, v19, v199
	v_add_f32_e32 v112, v112, v113
	v_max_f32_e64 v113, -v112, 0
	v_mul_f32_e64 v112, |v112|, s6
	v_exp_f32_e32 v112, v112
	v_cndmask_b32_e64 v111, 0, v111, s[44:45]
	v_add_f32_e32 v1, v1, v111
	v_add_f32_e32 v112, 1.0, v112
	v_cmp_gt_f32_e64 s[0:1], s7, v112
	s_nop 1
	v_cndmask_b32_e64 v114, 0, 32, s[0:1]
	v_ldexp_f32 v112, v112, v114
	v_log_f32_e32 v112, v112
	s_nop 0
	v_mul_f32_e32 v114, 0x3f317217, v112
	v_fma_f32 v114, v112, s8, -v114
	v_fmac_f32_e32 v114, 0x3377d1cf, v112
	v_fmac_f32_e32 v114, 0x3f317217, v112
	v_cmp_lt_f32_e64 s[4:5], |v112|, s9
	s_nop 1
	v_cndmask_b32_e64 v112, v112, v114, s[4:5]
	v_cndmask_b32_e64 v114, 0, v226, s[0:1]
	v_sub_f32_e32 v112, v112, v114
	v_add_f32_e32 v112, v113, v112
	v_mov_b32_e32 v113, s93
	ds_read_b128 v[184:187], v113 offset:4096
	ds_read_b128 v[188:191], v113 offset:4112
	ds_read_b128 v[192:195], v113 offset:4128
	ds_read_b128 v[196:199], v113 offset:4144
	s_nop 0
	s_nop 0
	s_nop 0
	s_nop 0
	v_mul_f32_e32 v112, 0xbd800000, v112
	s_nop 0
	s_waitcnt lgkmcnt(3)
	v_mul_f32_e32 v113, v6, v185
	v_fmac_f32_e32 v113, v4, v184
	s_waitcnt lgkmcnt(2)
	v_mul_f32_e32 v114, v7, v189
	v_fmac_f32_e32 v113, v8, v186
	v_fmac_f32_e32 v114, v5, v188
	v_fmac_f32_e32 v113, v10, v187
	v_fmac_f32_e32 v114, v9, v190
	v_add_f32_e32 v113, v26, v113
	v_fmac_f32_e32 v114, v11, v191
	v_add_f32_e32 v113, v113, v114
	s_waitcnt lgkmcnt(1)
	v_mul_f32_e32 v114, v14, v193
	v_fmac_f32_e32 v114, v12, v192
	v_fmac_f32_e32 v114, v16, v194
	v_fmac_f32_e32 v114, v18, v195
	v_add_f32_e32 v113, v113, v114
	s_waitcnt lgkmcnt(0)
	v_mul_f32_e32 v114, v15, v197
	v_fmac_f32_e32 v114, v13, v196
	v_fmac_f32_e32 v114, v17, v198
	v_fmac_f32_e32 v114, v19, v199
	v_add_f32_e32 v113, v113, v114
	v_max_f32_e64 v114, -v113, 0
	v_mul_f32_e64 v113, |v113|, s6
	v_exp_f32_e32 v113, v113
	v_mov_b32_e32 v126, s92
	ds_read_b128 v[184:187], v126 offset:4096
	ds_read_b128 v[188:191], v126 offset:4112
	ds_read_b128 v[192:195], v126 offset:4128
	v_cndmask_b32_e64 v112, 0, v112, s[26:27]
	v_add_f32_e32 v1, v1, v112
	v_add_f32_e32 v113, 1.0, v113
	v_cmp_gt_f32_e64 s[0:1], s7, v113
	s_nop 1
	v_cndmask_b32_e64 v115, 0, 32, s[0:1]
	v_ldexp_f32 v113, v113, v115
	v_log_f32_e32 v113, v113
	s_nop 0
	v_mul_f32_e32 v115, 0x3f317217, v113
	v_fma_f32 v115, v113, s8, -v115
	v_fmac_f32_e32 v115, 0x3377d1cf, v113
	v_fmac_f32_e32 v115, 0x3f317217, v113
	v_cmp_lt_f32_e64 s[4:5], |v113|, s9
	s_nop 1
	v_cndmask_b32_e64 v113, v113, v115, s[4:5]
	v_cndmask_b32_e64 v115, 0, v226, s[0:1]
	v_sub_f32_e32 v113, v113, v115
	v_add_f32_e32 v113, v114, v113
	s_nop 0
	s_nop 0
	s_nop 0
	ds_read_b128 v[126:129], v126 offset:4144
	v_mul_f32_e32 v113, 0xbd800000, v113
	s_nop 0
	s_waitcnt lgkmcnt(3)
	v_mul_f32_e32 v115, v6, v185
	v_fmac_f32_e32 v115, v4, v184
	v_fmac_f32_e32 v115, v8, v186
	v_fmac_f32_e32 v115, v10, v187
	v_add_f32_e32 v114, v26, v115
	s_waitcnt lgkmcnt(2)
	v_mul_f32_e32 v115, v7, v189
	v_fmac_f32_e32 v115, v5, v188
	v_fmac_f32_e32 v115, v9, v190
	v_fmac_f32_e32 v115, v11, v191
	v_add_f32_e32 v118, v114, v115
	s_waitcnt lgkmcnt(0)
	v_mov_b32_e32 v115, v126
	v_mov_b32_e32 v126, v193
	v_mov_b32_e32 v114, v192
	v_pk_mul_f32 v[116:117], v[14:15], v[126:127]
	v_cndmask_b32_e64 v113, 0, v113, s[28:29]
	v_pk_fma_f32 v[114:115], v[12:13], v[114:115], v[116:117]
	v_mov_b32_e32 v116, v194
	v_mov_b32_e32 v117, v128
	v_pk_fma_f32 v[114:115], v[16:17], v[116:117], v[114:115]
	v_mov_b32_e32 v128, v195
	v_pk_fma_f32 v[114:115], v[18:19], v[128:129], v[114:115]
	v_add_f32_e32 v1, v1, v113
	v_add_f32_e32 v114, v118, v114
	v_add_f32_e32 v114, v114, v115
	v_max_f32_e64 v115, -v114, 0
	v_mul_f32_e64 v114, |v114|, s6
	v_exp_f32_e32 v114, v114
	s_nop 0
	v_add_f32_e32 v114, 1.0, v114
	v_cmp_gt_f32_e64 s[0:1], s7, v114
	s_nop 1
	v_cndmask_b32_e64 v116, 0, 32, s[0:1]
	v_ldexp_f32 v114, v114, v116
	v_log_f32_e32 v114, v114
	s_nop 0
	v_mul_f32_e32 v116, 0x3f317217, v114
	v_fma_f32 v116, v114, s8, -v116
	v_fmac_f32_e32 v116, 0x3377d1cf, v114
	v_fmac_f32_e32 v116, 0x3f317217, v114
	v_cmp_lt_f32_e64 s[4:5], |v114|, s9
	s_nop 1
	v_cndmask_b32_e64 v114, v114, v116, s[4:5]
	v_cndmask_b32_e64 v116, 0, v226, s[0:1]
	v_sub_f32_e32 v114, v114, v116
	v_readlane_b32 s0, v254, 19
	v_add_f32_e32 v114, v115, v114
	v_mul_f32_e32 v114, 0xbd800000, v114
	v_mov_b32_e32 v115, s0
	ds_read_b128 v[184:187], v115 offset:4096
	ds_read_b128 v[188:191], v115 offset:4112
	ds_read_b128 v[192:195], v115 offset:4128
	s_nop 0
	s_nop 0
	s_nop 0
	ds_read_b128 v[128:131], v115 offset:4144
	v_cndmask_b32_e64 v114, 0, v114, s[22:23]
	s_nop 0
	s_waitcnt lgkmcnt(3)
	v_mul_f32_e32 v115, v6, v185
	v_fmac_f32_e32 v115, v4, v184
	s_waitcnt lgkmcnt(2)
	v_mul_f32_e32 v116, v7, v189
	v_fmac_f32_e32 v115, v8, v186
	v_fmac_f32_e32 v116, v5, v188
	v_fmac_f32_e32 v115, v10, v187
	v_fmac_f32_e32 v116, v9, v190
	v_add_f32_e32 v115, v26, v115
	v_fmac_f32_e32 v116, v11, v191
	s_waitcnt lgkmcnt(0)
	v_mov_b32_e32 v117, v128
	v_mov_b32_e32 v128, v193
	v_add_f32_e32 v115, v115, v116
	v_mov_b32_e32 v116, v192
	v_pk_mul_f32 v[118:119], v[14:15], v[128:129]
	v_mov_b32_e32 v128, s96
	ds_read_b128 v[184:187], v128 offset:4096
	v_pk_fma_f32 v[116:117], v[12:13], v[116:117], v[118:119]
	v_mov_b32_e32 v118, v194
	v_mov_b32_e32 v119, v130
	v_pk_fma_f32 v[116:117], v[16:17], v[118:119], v[116:117]
	v_mov_b32_e32 v130, v195
	v_pk_fma_f32 v[116:117], v[18:19], v[130:131], v[116:117]
	v_add_f32_e32 v1, v1, v114
	v_add_f32_e32 v115, v115, v116
	v_add_f32_e32 v115, v115, v117
	v_max_f32_e64 v116, -v115, 0
	v_mul_f32_e64 v115, |v115|, s6
	v_exp_f32_e32 v115, v115
	s_nop 0
	v_add_f32_e32 v115, 1.0, v115
	v_cmp_gt_f32_e64 s[0:1], s7, v115
	s_nop 1
	v_cndmask_b32_e64 v117, 0, 32, s[0:1]
	v_ldexp_f32 v115, v115, v117
	v_log_f32_e32 v115, v115
	s_nop 0
	v_mul_f32_e32 v117, 0x3f317217, v115
	v_fma_f32 v117, v115, s8, -v117
	v_fmac_f32_e32 v117, 0x3377d1cf, v115
	v_fmac_f32_e32 v117, 0x3f317217, v115
	v_cmp_lt_f32_e64 s[4:5], |v115|, s9
	s_nop 1
	v_cndmask_b32_e64 v115, v115, v117, s[4:5]
	v_cndmask_b32_e64 v117, 0, v226, s[0:1]
	v_sub_f32_e32 v115, v115, v117
	v_add_f32_e32 v115, v116, v115
	s_nop 0
	ds_read_b128 v[188:191], v128 offset:4128
	ds_read_b128 v[120:123], v128 offset:4112
	s_nop 0
	ds_read_b128 v[128:131], v128 offset:4144
	v_mul_f32_e32 v115, 0xbd800000, v115
	s_nop 0
	s_waitcnt lgkmcnt(3)
	v_mov_b32_e32 v132, v184
	s_waitcnt lgkmcnt(1)
	v_mov_b32_e32 v133, v120
	v_mov_b32_e32 v120, v185
	v_pk_mul_f32 v[116:117], v[6:7], v[120:121]
	v_mov_b32_e32 v120, v186
	v_pk_fma_f32 v[116:117], v[4:5], v[132:133], v[116:117]
	v_mov_b32_e32 v121, v122
	v_pk_fma_f32 v[116:117], v[8:9], v[120:121], v[116:117]
	v_mov_b32_e32 v122, v187
	v_pk_fma_f32 v[116:117], v[10:11], v[122:123], v[116:117]
	v_cndmask_b32_e64 v115, 0, v115, s[10:11]
	v_add_f32_e32 v116, v26, v116
	v_add_f32_e32 v120, v116, v117
	s_waitcnt lgkmcnt(0)
	v_mov_b32_e32 v117, v128
	v_mov_b32_e32 v128, v189
	v_mov_b32_e32 v116, v188
	v_pk_mul_f32 v[118:119], v[14:15], v[128:129]
	v_add_f32_e32 v1, v1, v115
	v_pk_fma_f32 v[116:117], v[12:13], v[116:117], v[118:119]
	v_mov_b32_e32 v118, v190
	v_mov_b32_e32 v119, v130
	v_pk_fma_f32 v[116:117], v[16:17], v[118:119], v[116:117]
	v_mov_b32_e32 v130, v191
	v_pk_fma_f32 v[116:117], v[18:19], v[130:131], v[116:117]
	s_nop 0
	v_add_f32_e32 v116, v120, v116
	v_add_f32_e32 v116, v116, v117
	v_max_f32_e64 v117, -v116, 0
	v_mul_f32_e64 v116, |v116|, s6
	v_exp_f32_e32 v116, v116
	s_nop 0
	v_add_f32_e32 v116, 1.0, v116
	v_cmp_gt_f32_e64 s[0:1], s7, v116
	s_nop 1
	v_cndmask_b32_e64 v118, 0, 32, s[0:1]
	v_ldexp_f32 v116, v116, v118
	v_log_f32_e32 v116, v116
	s_nop 0
	v_mul_f32_e32 v118, 0x3f317217, v116
	v_fma_f32 v118, v116, s8, -v118
	v_fmac_f32_e32 v118, 0x3377d1cf, v116
	v_fmac_f32_e32 v118, 0x3f317217, v116
	v_cmp_lt_f32_e64 s[4:5], |v116|, s9
	s_nop 1
	v_cndmask_b32_e64 v116, v116, v118, s[4:5]
	v_cndmask_b32_e64 v118, 0, v226, s[0:1]
	v_sub_f32_e32 v116, v116, v118
	v_add_f32_e32 v116, v117, v116
	v_mov_b32_e32 v117, s68
	ds_read_b128 v[184:187], v117 offset:4096
	s_nop 0
	ds_read_b128 v[188:191], v117 offset:4128
	ds_read_b128 v[122:125], v117 offset:4112
	s_nop 0
	ds_read_b128 v[130:133], v117 offset:4144
	v_mul_f32_e32 v116, 0xbd800000, v116
	s_nop 0
	s_waitcnt lgkmcnt(3)
	v_mov_b32_e32 v134, v184
	s_waitcnt lgkmcnt(1)
	v_mov_b32_e32 v135, v122
	v_mov_b32_e32 v122, v185
	v_pk_mul_f32 v[118:119], v[6:7], v[122:123]
	v_mov_b32_e32 v122, v186
	v_pk_fma_f32 v[118:119], v[4:5], v[134:135], v[118:119]
	v_mov_b32_e32 v123, v124
	v_pk_fma_f32 v[118:119], v[8:9], v[122:123], v[118:119]
	v_mov_b32_e32 v124, v187
	v_pk_fma_f32 v[118:119], v[10:11], v[124:125], v[118:119]
	v_cndmask_b32_e64 v116, 0, v116, s[18:19]
	v_add_f32_e32 v117, v26, v118
	v_add_f32_e32 v117, v117, v119
	s_waitcnt lgkmcnt(0)
	v_mov_b32_e32 v119, v130
	v_mov_b32_e32 v130, v189
	v_mov_b32_e32 v118, v188
	v_pk_mul_f32 v[120:121], v[14:15], v[130:131]
	v_mov_b32_e32 v130, s66
	ds_read_b128 v[184:187], v130 offset:4096
	v_pk_fma_f32 v[118:119], v[12:13], v[118:119], v[120:121]
	v_mov_b32_e32 v120, v190
	v_mov_b32_e32 v121, v132
	v_pk_fma_f32 v[118:119], v[16:17], v[120:121], v[118:119]
	v_mov_b32_e32 v132, v191
	v_pk_fma_f32 v[118:119], v[18:19], v[132:133], v[118:119]
	v_add_f32_e32 v1, v1, v116
	v_add_f32_e32 v117, v117, v118
	v_add_f32_e32 v117, v117, v119
	v_max_f32_e64 v118, -v117, 0
	v_mul_f32_e64 v117, |v117|, s6
	v_exp_f32_e32 v117, v117
	s_nop 0
	v_add_f32_e32 v117, 1.0, v117
	v_cmp_gt_f32_e64 s[0:1], s7, v117
	s_nop 1
	v_cndmask_b32_e64 v119, 0, 32, s[0:1]
	v_ldexp_f32 v117, v117, v119
	v_log_f32_e32 v117, v117
	s_nop 0
	v_mul_f32_e32 v119, 0x3f317217, v117
	v_fma_f32 v119, v117, s8, -v119
	v_fmac_f32_e32 v119, 0x3377d1cf, v117
	v_fmac_f32_e32 v119, 0x3f317217, v117
	v_cmp_lt_f32_e64 s[4:5], |v117|, s9
	s_nop 1
	v_cndmask_b32_e64 v117, v117, v119, s[4:5]
	v_cndmask_b32_e64 v119, 0, v226, s[0:1]
	v_sub_f32_e32 v117, v117, v119
	v_add_f32_e32 v117, v118, v117
	s_nop 0
	ds_read_b128 v[188:191], v130 offset:4128
	ds_read_b128 v[122:125], v130 offset:4112
	s_nop 0
	ds_read_b128 v[130:133], v130 offset:4144
	v_mul_f32_e32 v117, 0xbd800000, v117
	s_nop 0
	s_waitcnt lgkmcnt(3)
	v_mov_b32_e32 v134, v184
	s_waitcnt lgkmcnt(1)
	v_mov_b32_e32 v135, v122
	v_mov_b32_e32 v122, v185
	v_pk_mul_f32 v[118:119], v[6:7], v[122:123]
	v_mov_b32_e32 v122, v186
	v_pk_fma_f32 v[118:119], v[4:5], v[134:135], v[118:119]
	v_mov_b32_e32 v123, v124
	v_pk_fma_f32 v[118:119], v[8:9], v[122:123], v[118:119]
	v_mov_b32_e32 v124, v187
	v_pk_fma_f32 v[118:119], v[10:11], v[124:125], v[118:119]
	v_cndmask_b32_e64 v117, 0, v117, s[20:21]
	v_add_f32_e32 v118, v26, v118
	v_add_f32_e32 v122, v118, v119
	s_waitcnt lgkmcnt(0)
	v_mov_b32_e32 v119, v130
	v_mov_b32_e32 v130, v189
	v_mov_b32_e32 v118, v188
	v_pk_mul_f32 v[120:121], v[14:15], v[130:131]
	v_add_f32_e32 v1, v1, v117
	v_pk_fma_f32 v[118:119], v[12:13], v[118:119], v[120:121]
	v_mov_b32_e32 v120, v190
	v_mov_b32_e32 v121, v132
	v_pk_fma_f32 v[118:119], v[16:17], v[120:121], v[118:119]
	v_mov_b32_e32 v132, v191
	v_pk_fma_f32 v[118:119], v[18:19], v[132:133], v[118:119]
	s_nop 0
	v_add_f32_e32 v118, v122, v118
	v_add_f32_e32 v118, v118, v119
	v_max_f32_e64 v119, -v118, 0
	v_mul_f32_e64 v118, |v118|, s6
	v_exp_f32_e32 v118, v118
	s_nop 0
	v_add_f32_e32 v118, 1.0, v118
	v_cmp_gt_f32_e64 s[0:1], s7, v118
	s_nop 1
	v_cndmask_b32_e64 v120, 0, 32, s[0:1]
	v_ldexp_f32 v118, v118, v120
	v_log_f32_e32 v118, v118
	s_nop 0
	v_mul_f32_e32 v120, 0x3f317217, v118
	v_fma_f32 v120, v118, s8, -v120
	v_fmac_f32_e32 v120, 0x3377d1cf, v118
	v_fmac_f32_e32 v120, 0x3f317217, v118
	v_cmp_lt_f32_e64 s[4:5], |v118|, s9
	s_nop 1
	v_cndmask_b32_e64 v118, v118, v120, s[4:5]
	v_cndmask_b32_e64 v120, 0, v226, s[0:1]
	v_sub_f32_e32 v118, v118, v120
	v_add_f32_e32 v118, v119, v118
	v_mov_b32_e32 v119, s60
	ds_read_b128 v[120:123], v119 offset:4096
	ds_read_b128 v[124:127], v119 offset:4112
	ds_read_b128 v[128:131], v119 offset:4128
	ds_read_b128 v[132:135], v119 offset:4144
	v_mul_f32_e32 v118, 0xbd800000, v118
	s_nop 0
	s_waitcnt lgkmcnt(3)
	v_mov_b32_e32 v136, v120
	s_waitcnt lgkmcnt(2)
	v_mov_b32_e32 v137, v124
	v_mov_b32_e32 v124, v121
	v_pk_mul_f32 v[6:7], v[6:7], v[124:125]
	v_cndmask_b32_e64 v118, 0, v118, s[12:13]
	v_pk_fma_f32 v[4:5], v[4:5], v[136:137], v[6:7]
	v_mov_b32_e32 v6, v122
	v_mov_b32_e32 v7, v126
	v_pk_fma_f32 v[4:5], v[8:9], v[6:7], v[4:5]
	v_mov_b32_e32 v126, v123
	v_pk_fma_f32 v[4:5], v[10:11], v[126:127], v[4:5]
	v_add_f32_e32 v1, v1, v118
	v_add_f32_e32 v4, v26, v4
	v_add_f32_e32 v8, v4, v5
	s_waitcnt lgkmcnt(0)
	v_mov_b32_e32 v5, v132
	v_mov_b32_e32 v132, v129
	v_mov_b32_e32 v4, v128
	v_pk_mul_f32 v[6:7], v[14:15], v[132:133]
	s_nop 0
	v_pk_fma_f32 v[4:5], v[12:13], v[4:5], v[6:7]
	v_mov_b32_e32 v6, v130
	v_mov_b32_e32 v7, v134
	v_pk_fma_f32 v[4:5], v[16:17], v[6:7], v[4:5]
	v_mov_b32_e32 v134, v131
	v_pk_fma_f32 v[4:5], v[18:19], v[134:135], v[4:5]
	s_nop 0
	v_add_f32_e32 v4, v8, v4
	v_add_f32_e32 v4, v4, v5
	v_max_f32_e64 v5, -v4, 0
	v_mul_f32_e64 v4, |v4|, s6
	v_exp_f32_e32 v4, v4
	s_nop 0
	v_add_f32_e32 v4, 1.0, v4
	v_cmp_gt_f32_e64 s[0:1], s7, v4
	s_mov_b64 s[6:7], s[88:89]
	s_nop 0
	v_cndmask_b32_e64 v6, 0, 32, s[0:1]
	v_ldexp_f32 v4, v4, v6
	v_log_f32_e32 v4, v4
	s_nop 0
	v_mul_f32_e32 v6, 0x3f317217, v4
	v_fma_f32 v6, v4, s8, -v6
	v_fmac_f32_e32 v6, 0x3377d1cf, v4
	v_fmac_f32_e32 v6, 0x3f317217, v4
	v_cmp_lt_f32_e64 s[4:5], |v4|, s9
	s_nop 1
	v_cndmask_b32_e64 v4, v4, v6, s[4:5]
	v_cndmask_b32_e64 v6, 0, v226, s[0:1]
	v_sub_f32_e32 v4, v4, v6
	v_readlane_b32 s4, v253, 10
	v_add_f32_e32 v4, v5, v4
	v_readlane_b32 s5, v253, 11
	v_mul_f32_e32 v4, 0xbd800000, v4
	v_lshl_add_u64 v[6:7], s[84:85], 0, v[2:3]
	v_cndmask_b32_e64 v12, 0, v4, s[4:5]
	v_lshlrev_b32_sdwa v4, v228, v25 dst_sel:DWORD dst_unused:UNUSED_PAD src0_sel:DWORD src1_sel:BYTE_0
	v_add_f32_e32 v1, v1, v12
	v_add_u32_e32 v5, s50, v4
	ds_write_b32 v5, v1
	v_add_u32_e32 v1, 0, v4
	s_waitcnt lgkmcnt(0)
	s_barrier
	ds_read2st64_b32 v[4:5], v1 offset1:4
	v_lshl_add_u64 v[2:3], s[86:87], 0, v[2:3]
	s_waitcnt lgkmcnt(0)
	v_cndmask_b32_e64 v1, v4, 0, s[6:7]
	v_add_f32_e32 v9, v22, v1
	v_sub_f32_e32 v1, v4, v9
	v_mul_f32_e32 v1, 0x3fb8aa3b, v1
	v_exp_f32_e32 v1, v1
	s_nop 0
	v_mul_f32_e32 v8, v1, v89
	s_cbranch_scc1 .LBB0_531
	v_sub_f32_e32 v1, v9, v4
	v_mul_f32_e32 v1, 0x3fb8aa3b, v1
	v_exp_f32_e32 v1, v1
	v_lshlrev_b32_e32 v10, 16, v86
	v_mul_f32_e32 v1, v1, v10
	v_cvt_pk_bf16_f32 v1, v1, s0
	s_lshl_b64 s[0:1], s[38:39], 11
	v_lshl_add_u64 v[10:11], v[6:7], 0, s[0:1]
	global_store_short v[10:11], v1, off
	v_cvt_pk_bf16_f32 v1, v8, s0
	v_lshl_add_u64 v[10:11], v[2:3], 0, s[0:1]
	global_store_short v[10:11], v1, off
.LBB0_531:
	v_add_f32_e32 v10, v23, v9
	v_sub_f32_e32 v9, v4, v10
	v_mul_f32_e32 v9, 0x3fb8aa3b, v9
	v_exp_f32_e32 v9, v9
	v_lshlrev_b32_e32 v1, 16, v88
	v_cndmask_b32_e64 v1, 0, v1, s[82:83]
	s_andn2_b64 vcc, exec, s[82:83]
	v_mul_f32_e32 v9, v9, v1
	s_cbranch_vccnz .LBB0_533
	v_sub_f32_e32 v1, v10, v4
	v_mul_f32_e32 v1, 0x3fb8aa3b, v1
	v_exp_f32_e32 v1, v1
	v_lshlrev_b32_e32 v11, 16, v84
	s_ashr_i32 s73, s72, 31
	s_lshl_b64 s[0:1], s[72:73], 11
	v_mul_f32_e32 v1, v1, v11
	v_cvt_pk_bf16_f32 v1, v1, s0
	v_lshl_add_u64 v[14:15], v[6:7], 0, s[0:1]
	global_store_short v[14:15], v1, off
	v_cvt_pk_bf16_f32 v1, v9, s0
	v_lshl_add_u64 v[14:15], v[2:3], 0, s[0:1]
	global_store_short v[14:15], v1, off
.LBB0_533:
	v_add_f32_e32 v11, v90, v10
	v_sub_f32_e32 v10, v4, v11
	v_mul_f32_e32 v10, 0x3fb8aa3b, v10
	v_exp_f32_e32 v10, v10
	v_lshlrev_b32_e32 v1, 16, v87
	v_cndmask_b32_e64 v1, 0, v1, s[2:3]
	s_andn2_b64 vcc, exec, s[2:3]
	v_mul_f32_e32 v10, v10, v1
	s_mov_b64 s[2:3], 0x80
	s_cbranch_vccnz .LBB0_535
	v_sub_f32_e32 v1, v11, v4
	v_mul_f32_e32 v1, 0x3fb8aa3b, v1
	v_exp_f32_e32 v1, v1
	v_readlane_b32 s0, v252, 33
	v_readlane_b32 s1, v252, 34
	v_lshlrev_b32_e32 v13, 16, v82
	s_ashr_i32 s1, s0, 31
	s_lshl_b64 s[0:1], s[0:1], 11
	v_mul_f32_e32 v1, v1, v13
	v_cvt_pk_bf16_f32 v1, v1, s0
	v_lshl_add_u64 v[14:15], v[6:7], 0, s[0:1]
	global_store_short v[14:15], v1, off
	v_cvt_pk_bf16_f32 v1, v10, s0
	v_lshl_add_u64 v[14:15], v[2:3], 0, s[0:1]
	global_store_short v[14:15], v1, off
.LBB0_535:
	v_add_f32_e32 v13, v91, v11
	v_sub_f32_e32 v11, v4, v13
	v_mul_f32_e32 v11, 0x3fb8aa3b, v11
	v_exp_f32_e32 v11, v11
	v_lshlrev_b32_e32 v1, 16, v85
	v_cndmask_b32_e64 v1, 0, v1, s[80:81]
	s_andn2_b64 vcc, exec, s[80:81]
	v_mul_f32_e32 v11, v11, v1
	s_cbranch_vccnz .LBB0_537
	v_sub_f32_e32 v1, v13, v4
	v_mul_f32_e32 v1, 0x3fb8aa3b, v1
	v_exp_f32_e32 v1, v1
	v_readlane_b32 s0, v252, 31
	v_readlane_b32 s1, v252, 32
	v_lshlrev_b32_e32 v14, 16, v80
	s_ashr_i32 s1, s0, 31
	s_lshl_b64 s[0:1], s[0:1], 11
	v_mul_f32_e32 v1, v1, v14
	v_cvt_pk_bf16_f32 v1, v1, s0
	v_lshl_add_u64 v[14:15], v[6:7], 0, s[0:1]
	global_store_short v[14:15], v1, off
	v_cvt_pk_bf16_f32 v1, v11, s0
	v_lshl_add_u64 v[14:15], v[2:3], 0, s[0:1]
	global_store_short v[14:15], v1, off
.LBB0_537:
	v_add_f32_e32 v13, v92, v13
	v_sub_f32_e32 v14, v4, v13
	v_mul_f32_e32 v14, 0x3fb8aa3b, v14
	v_exp_f32_e32 v14, v14
	v_lshlrev_b32_e32 v1, 16, v83
	v_cndmask_b32_e64 v1, 0, v1, s[78:79]
	s_andn2_b64 vcc, exec, s[78:79]
	v_mul_f32_e32 v14, v14, v1
	s_cbranch_vccnz .LBB0_539
	v_sub_f32_e32 v1, v13, v4
	v_mul_f32_e32 v1, 0x3fb8aa3b, v1
	v_exp_f32_e32 v1, v1
	v_readlane_b32 s0, v254, 25
	v_readlane_b32 s1, v254, 26
	v_lshlrev_b32_e32 v15, 16, v79
	s_ashr_i32 s1, s0, 31
	s_lshl_b64 s[0:1], s[0:1], 11
	v_mul_f32_e32 v1, v1, v15
	v_cvt_pk_bf16_f32 v1, v1, s0
	v_lshl_add_u64 v[16:17], v[6:7], 0, s[0:1]
	global_store_short v[16:17], v1, off
	v_cvt_pk_bf16_f32 v1, v14, s0
	v_lshl_add_u64 v[16:17], v[2:3], 0, s[0:1]
	global_store_short v[16:17], v1, off
.LBB0_539:
	v_add_f32_e32 v13, v93, v13
	v_sub_f32_e32 v15, v4, v13
	v_mul_f32_e32 v15, 0x3fb8aa3b, v15
	v_exp_f32_e32 v15, v15
	v_lshlrev_b32_e32 v1, 16, v81
	v_cndmask_b32_e64 v1, 0, v1, s[76:77]
	s_andn2_b64 vcc, exec, s[76:77]
	v_mul_f32_e32 v15, v15, v1
	s_cbranch_vccnz .LBB0_541
	v_sub_f32_e32 v1, v13, v4
	v_mul_f32_e32 v1, 0x3fb8aa3b, v1
	v_exp_f32_e32 v1, v1
	v_readlane_b32 s0, v254, 27
	v_readlane_b32 s1, v254, 28
	v_lshlrev_b32_e32 v16, 16, v77
	s_ashr_i32 s1, s0, 31
	s_lshl_b64 s[0:1], s[0:1], 11
	v_mul_f32_e32 v1, v1, v16
	v_cvt_pk_bf16_f32 v1, v1, s0
	v_lshl_add_u64 v[16:17], v[6:7], 0, s[0:1]
	global_store_short v[16:17], v1, off
	v_cvt_pk_bf16_f32 v1, v15, s0
	v_lshl_add_u64 v[16:17], v[2:3], 0, s[0:1]
	global_store_short v[16:17], v1, off
.LBB0_541:
	v_add_f32_e32 v13, v94, v13
	v_sub_f32_e32 v16, v4, v13
	v_mul_f32_e32 v16, 0x3fb8aa3b, v16
	v_exp_f32_e32 v16, v16
	v_lshlrev_b32_e32 v1, 16, v78
	v_cndmask_b32_e64 v1, 0, v1, s[74:75]
	s_andn2_b64 vcc, exec, s[74:75]
	v_mul_f32_e32 v17, v16, v1
	s_cbranch_vccnz .LBB0_543
	v_sub_f32_e32 v1, v13, v4
	v_mul_f32_e32 v1, 0x3fb8aa3b, v1
	v_exp_f32_e32 v1, v1
	v_readlane_b32 s0, v254, 31
	v_readlane_b32 s1, v254, 32
	v_lshlrev_b32_e32 v16, 16, v75
	s_ashr_i32 s1, s0, 31
	s_lshl_b64 s[0:1], s[0:1], 11
	v_mul_f32_e32 v1, v1, v16
	v_cvt_pk_bf16_f32 v1, v1, s0
	v_lshl_add_u64 v[18:19], v[6:7], 0, s[0:1]
	global_store_short v[18:19], v1, off
	v_cvt_pk_bf16_f32 v1, v17, s0
	v_lshl_add_u64 v[18:19], v[2:3], 0, s[0:1]
	global_store_short v[18:19], v1, off
.LBB0_543:
	v_add_f32_e32 v16, v95, v13
	v_sub_f32_e32 v13, v4, v16
	v_mul_f32_e32 v13, 0x3fb8aa3b, v13
	v_exp_f32_e32 v13, v13
	v_lshlrev_b32_e32 v1, 16, v76
	v_cndmask_b32_e64 v1, 0, v1, s[70:71]
	s_andn2_b64 vcc, exec, s[70:71]
	v_mul_f32_e32 v18, v13, v1
	s_cbranch_vccnz .LBB0_545
	v_sub_f32_e32 v1, v16, v4
	v_mul_f32_e32 v1, 0x3fb8aa3b, v1
	v_exp_f32_e32 v1, v1
	v_readlane_b32 s0, v254, 29
	v_readlane_b32 s1, v254, 30
	v_lshlrev_b32_e32 v13, 16, v73
	s_ashr_i32 s1, s0, 31
	s_lshl_b64 s[0:1], s[0:1], 11
	v_mul_f32_e32 v1, v1, v13
	v_cvt_pk_bf16_f32 v1, v1, s0
	v_lshl_add_u64 v[22:23], v[6:7], 0, s[0:1]
	global_store_short v[22:23], v1, off
	v_cvt_pk_bf16_f32 v1, v18, s0
	v_lshl_add_u64 v[22:23], v[2:3], 0, s[0:1]
	global_store_short v[22:23], v1, off
.LBB0_545:
	v_add_f32_e32 v5, v4, v5
	v_sub_f32_e32 v1, v5, v4
	v_mul_f32_e32 v1, 0x3fb8aa3b, v1
	v_exp_f32_e32 v13, v1
	s_ashr_i32 s17, s16, 31
	s_lshl_b64 s[0:1], s[16:17], 10
	s_andn2_b64 vcc, exec, s[62:63]
	v_mul_f32_e32 v14, v13, v14
	v_mul_f32_e32 v15, v13, v15
	v_mul_f32_e32 v22, v13, v8
	v_lshlrev_b32_e32 v8, 16, v74
	v_mul_f32_e32 v1, v13, v17
	v_cndmask_b32_e64 v26, 0, v8, s[62:63]
	v_or_b32_e32 v8, s0, v24
	v_mul_f32_e32 v18, v13, v18
	v_cvt_pk_bf16_f32 v24, v14, v15
	v_add_f32_e32 v15, v96, v16
	v_cvt_pk_bf16_f32 v25, v1, v18
	v_sub_f32_e32 v1, v4, v15
	v_mul_f32_e32 v1, 0x3fb8aa3b, v1
	v_exp_f32_e32 v1, v1
	v_mul_f32_e32 v23, v13, v9
	v_mov_b32_e32 v9, s1
	v_readlane_b32 s0, v252, 47
	v_mul_f32_e32 v17, v13, v10
	v_mul_f32_e32 v19, v13, v11
	v_lshlrev_b64 v[10:11], 7, v[8:9]
	v_readlane_b32 s1, v252, 48
	v_cvt_pk_bf16_f32 v22, v22, v23
	v_cvt_pk_bf16_f32 v23, v17, v19
	v_lshl_add_u64 v[10:11], s[0:1], 0, v[10:11]
	v_lshl_add_u64 v[10:11], s[38:39], 1, v[10:11]
	v_mul_f32_e32 v14, v1, v26
	global_store_dwordx4 v[10:11], v[22:25], off
	s_cbranch_vccnz .LBB0_547
	v_sub_f32_e32 v1, v15, v4
	v_mul_f32_e32 v1, 0x3fb8aa3b, v1
	v_exp_f32_e32 v1, v1
	v_readlane_b32 s0, v254, 33
	v_readlane_b32 s1, v254, 34
	v_lshlrev_b32_e32 v16, 16, v69
	s_ashr_i32 s1, s0, 31
	s_lshl_b64 s[0:1], s[0:1], 11
	v_mul_f32_e32 v1, v1, v16
	v_cvt_pk_bf16_f32 v1, v1, s0
	v_lshl_add_u64 v[16:17], v[6:7], 0, s[0:1]
	global_store_short v[16:17], v1, off
	v_cvt_pk_bf16_f32 v1, v14, s0
	v_lshl_add_u64 v[16:17], v[2:3], 0, s[0:1]
	global_store_short v[16:17], v1, off
.LBB0_547:
	v_add_f32_e32 v16, v97, v15
	v_sub_f32_e32 v15, v4, v16
	v_mul_f32_e32 v15, 0x3fb8aa3b, v15
	v_exp_f32_e32 v15, v15
	v_lshlrev_b32_e32 v1, 16, v72
	v_cndmask_b32_e64 v1, 0, v1, s[64:65]
	s_andn2_b64 vcc, exec, s[64:65]
	v_mul_f32_e32 v15, v15, v1
	s_cbranch_vccnz .LBB0_549
	v_sub_f32_e32 v1, v16, v4
	v_mul_f32_e32 v1, 0x3fb8aa3b, v1
	v_exp_f32_e32 v1, v1
	v_readlane_b32 s0, v254, 35
	v_readlane_b32 s1, v254, 36
	v_lshlrev_b32_e32 v17, 16, v70
	s_ashr_i32 s1, s0, 31
	s_lshl_b64 s[0:1], s[0:1], 11
	v_mul_f32_e32 v1, v1, v17
	v_cvt_pk_bf16_f32 v1, v1, s0
	v_lshl_add_u64 v[18:19], v[6:7], 0, s[0:1]
	global_store_short v[18:19], v1, off
	v_cvt_pk_bf16_f32 v1, v15, s0
	v_lshl_add_u64 v[18:19], v[2:3], 0, s[0:1]
	global_store_short v[18:19], v1, off
.LBB0_549:
	v_add_f32_e32 v17, v98, v16
	v_sub_f32_e32 v16, v4, v17
	v_mul_f32_e32 v16, 0x3fb8aa3b, v16
	v_exp_f32_e32 v16, v16
	v_lshlrev_b32_e32 v1, 16, v71
	v_cndmask_b32_e64 v1, 0, v1, s[58:59]
	s_andn2_b64 vcc, exec, s[58:59]
	v_mul_f32_e32 v16, v16, v1
	s_cbranch_vccnz .LBB0_551
	v_sub_f32_e32 v1, v17, v4
	v_mul_f32_e32 v1, 0x3fb8aa3b, v1
	v_exp_f32_e32 v1, v1
	v_readlane_b32 s0, v254, 37
	v_readlane_b32 s1, v254, 38
	v_lshlrev_b32_e32 v18, 16, v67
	s_ashr_i32 s1, s0, 31
	s_lshl_b64 s[0:1], s[0:1], 11
	v_mul_f32_e32 v1, v1, v18
	v_cvt_pk_bf16_f32 v1, v1, s0
	v_lshl_add_u64 v[18:19], v[6:7], 0, s[0:1]
	global_store_short v[18:19], v1, off
	v_cvt_pk_bf16_f32 v1, v16, s0
	v_lshl_add_u64 v[18:19], v[2:3], 0, s[0:1]
	global_store_short v[18:19], v1, off
.LBB0_551:
	v_add_f32_e32 v18, v99, v17
	v_sub_f32_e32 v17, v4, v18
	v_mul_f32_e32 v17, 0x3fb8aa3b, v17
	v_exp_f32_e32 v17, v17
	v_lshlrev_b32_e32 v1, 16, v68
	v_cndmask_b32_e64 v1, 0, v1, s[56:57]
	s_andn2_b64 vcc, exec, s[56:57]
	v_mul_f32_e32 v17, v17, v1
	s_cbranch_vccnz .LBB0_553
	v_sub_f32_e32 v1, v18, v4
	v_mul_f32_e32 v1, 0x3fb8aa3b, v1
	v_exp_f32_e32 v1, v1
	v_readlane_b32 s0, v254, 39
	v_readlane_b32 s1, v254, 40
	v_lshlrev_b32_e32 v19, 16, v65
	s_ashr_i32 s1, s0, 31
	s_lshl_b64 s[0:1], s[0:1], 11
	v_mul_f32_e32 v1, v1, v19
	v_cvt_pk_bf16_f32 v1, v1, s0
	v_lshl_add_u64 v[22:23], v[6:7], 0, s[0:1]
	global_store_short v[22:23], v1, off
	v_cvt_pk_bf16_f32 v1, v17, s0
	v_lshl_add_u64 v[22:23], v[2:3], 0, s[0:1]
	global_store_short v[22:23], v1, off
.LBB0_553:
	v_add_f32_e32 v19, v100, v18
	v_sub_f32_e32 v18, v4, v19
	v_mul_f32_e32 v18, 0x3fb8aa3b, v18
	v_exp_f32_e32 v18, v18
	v_lshlrev_b32_e32 v1, 16, v66
	v_cndmask_b32_e64 v1, 0, v1, s[54:55]
	s_andn2_b64 vcc, exec, s[54:55]
	v_mul_f32_e32 v18, v18, v1
	s_cbranch_vccnz .LBB0_555
	v_sub_f32_e32 v1, v19, v4
	v_mul_f32_e32 v1, 0x3fb8aa3b, v1
	v_exp_f32_e32 v1, v1
	v_readlane_b32 s0, v254, 41
	v_readlane_b32 s1, v254, 42
	v_lshlrev_b32_e32 v22, 16, v63
	s_ashr_i32 s1, s0, 31
	s_lshl_b64 s[0:1], s[0:1], 11
	v_mul_f32_e32 v1, v1, v22
	v_cvt_pk_bf16_f32 v1, v1, s0
	v_lshl_add_u64 v[22:23], v[6:7], 0, s[0:1]
	global_store_short v[22:23], v1, off
	v_cvt_pk_bf16_f32 v1, v18, s0
	v_lshl_add_u64 v[22:23], v[2:3], 0, s[0:1]
	global_store_short v[22:23], v1, off
.LBB0_555:
	v_add_f32_e32 v22, v101, v19
	v_sub_f32_e32 v19, v4, v22
	v_mul_f32_e32 v19, 0x3fb8aa3b, v19
	v_exp_f32_e32 v19, v19
	s_waitcnt vmcnt(0)
	v_lshlrev_b32_e32 v1, 16, v64
	v_cndmask_b32_e64 v1, 0, v1, s[52:53]
	s_andn2_b64 vcc, exec, s[52:53]
	v_mul_f32_e32 v19, v19, v1
	s_cbranch_vccnz .LBB0_557
	v_sub_f32_e32 v1, v22, v4
	v_mul_f32_e32 v1, 0x3fb8aa3b, v1
	v_exp_f32_e32 v1, v1
	v_readlane_b32 s0, v254, 43
	v_readlane_b32 s1, v254, 44
	v_lshlrev_b32_e32 v23, 16, v61
	s_ashr_i32 s1, s0, 31
	s_lshl_b64 s[0:1], s[0:1], 11
	v_mul_f32_e32 v1, v1, v23
	v_cvt_pk_bf16_f32 v1, v1, s0
	v_lshl_add_u64 v[24:25], v[6:7], 0, s[0:1]
	global_store_short v[24:25], v1, off
	v_cvt_pk_bf16_f32 v1, v19, s0
	v_lshl_add_u64 v[24:25], v[2:3], 0, s[0:1]
	global_store_short v[24:25], v1, off
.LBB0_557:
	v_add_f32_e32 v23, v102, v22
	v_sub_f32_e32 v22, v4, v23
	v_mul_f32_e32 v22, 0x3fb8aa3b, v22
	v_exp_f32_e32 v22, v22
	v_lshlrev_b32_e32 v1, 16, v62
	v_cndmask_b32_e64 v1, 0, v1, s[48:49]
	s_andn2_b64 vcc, exec, s[48:49]
	v_mul_f32_e32 v22, v22, v1
	s_cbranch_vccnz .LBB0_559
	v_sub_f32_e32 v1, v23, v4
	v_mul_f32_e32 v1, 0x3fb8aa3b, v1
	v_exp_f32_e32 v1, v1
	v_readlane_b32 s0, v254, 45
	v_readlane_b32 s1, v254, 46
	v_lshlrev_b32_e32 v24, 16, v59
	s_ashr_i32 s1, s0, 31
	s_lshl_b64 s[0:1], s[0:1], 11
	v_mul_f32_e32 v1, v1, v24
	v_cvt_pk_bf16_f32 v1, v1, s0
	v_lshl_add_u64 v[24:25], v[6:7], 0, s[0:1]
	global_store_short v[24:25], v1, off
	v_cvt_pk_bf16_f32 v1, v22, s0
	v_lshl_add_u64 v[24:25], v[2:3], 0, s[0:1]
	global_store_short v[24:25], v1, off
.LBB0_559:
	v_add_f32_e32 v23, v103, v23
	v_sub_f32_e32 v24, v4, v23
	v_mul_f32_e32 v24, 0x3fb8aa3b, v24
	v_exp_f32_e32 v24, v24
	v_lshlrev_b32_e32 v1, 16, v60
	v_cndmask_b32_e64 v1, 0, v1, s[46:47]
	s_andn2_b64 vcc, exec, s[46:47]
	v_mul_f32_e32 v24, v24, v1
	s_cbranch_vccnz .LBB0_561
	v_sub_f32_e32 v1, v23, v4
	v_mul_f32_e32 v1, 0x3fb8aa3b, v1
	v_exp_f32_e32 v1, v1
	v_readlane_b32 s0, v254, 47
	v_readlane_b32 s1, v254, 48
	v_lshlrev_b32_e32 v25, 16, v57
	s_ashr_i32 s1, s0, 31
	s_lshl_b64 s[0:1], s[0:1], 11
	v_mul_f32_e32 v1, v1, v25
	v_cvt_pk_bf16_f32 v1, v1, s0
	v_lshl_add_u64 v[60:61], v[6:7], 0, s[0:1]
	global_store_short v[60:61], v1, off
	v_cvt_pk_bf16_f32 v1, v24, s0
	v_lshl_add_u64 v[60:61], v[2:3], 0, s[0:1]
	global_store_short v[60:61], v1, off
.LBB0_561:
	v_mul_f32_e32 v1, v13, v22
	v_mul_f32_e32 v18, v13, v18
	v_mul_f32_e32 v19, v13, v19
	v_mul_f32_e32 v16, v13, v16
	v_mul_f32_e32 v17, v13, v17
	v_mul_f32_e32 v14, v13, v14
	v_mul_f32_e32 v15, v13, v15
	v_mul_f32_e32 v24, v13, v24
	v_cvt_pk_bf16_f32 v14, v14, v15
	v_cvt_pk_bf16_f32 v15, v16, v17
	v_cvt_pk_bf16_f32 v16, v18, v19
	v_cvt_pk_bf16_f32 v17, v1, v24
	global_store_dwordx4 v[10:11], v[14:17], off offset:16
	v_lshlrev_b32_e32 v22, 16, v58
	v_cndmask_b32_e64 v22, 0, v22, s[42:43]
	v_add_f32_e32 v15, v104, v23
	v_sub_f32_e32 v1, v4, v15
	v_mul_f32_e32 v1, 0x3fb8aa3b, v1
	v_exp_f32_e32 v1, v1
	s_andn2_b64 vcc, exec, s[42:43]
	v_mul_f32_e32 v14, v1, v22
	s_cbranch_vccnz .LBB0_563
	v_sub_f32_e32 v1, v15, v4
	v_mul_f32_e32 v1, 0x3fb8aa3b, v1
	v_exp_f32_e32 v1, v1
	v_readlane_b32 s0, v254, 50
	v_readlane_b32 s1, v254, 51
	v_lshlrev_b32_e32 v16, 16, v43
	s_ashr_i32 s1, s0, 31
	s_lshl_b64 s[0:1], s[0:1], 11
	v_mul_f32_e32 v1, v1, v16
	v_cvt_pk_bf16_f32 v1, v1, s0
	v_lshl_add_u64 v[16:17], v[6:7], 0, s[0:1]
	global_store_short v[16:17], v1, off
	v_cvt_pk_bf16_f32 v1, v14, s0
	v_lshl_add_u64 v[16:17], v[2:3], 0, s[0:1]
	global_store_short v[16:17], v1, off
.LBB0_563:
	v_add_f32_e32 v16, v105, v15
	v_sub_f32_e32 v15, v4, v16
	v_mul_f32_e32 v15, 0x3fb8aa3b, v15
	v_exp_f32_e32 v15, v15
	v_lshlrev_b32_e32 v1, 16, v50
	v_cndmask_b32_e64 v1, 0, v1, s[14:15]
	s_andn2_b64 vcc, exec, s[14:15]
	v_mul_f32_e32 v15, v15, v1
	s_cbranch_vccnz .LBB0_565
	v_sub_f32_e32 v1, v16, v4
	v_mul_f32_e32 v1, 0x3fb8aa3b, v1
	v_exp_f32_e32 v1, v1
	v_readlane_b32 s0, v254, 53
	v_readlane_b32 s1, v254, 54
	v_lshlrev_b32_e32 v17, 16, v35
	s_ashr_i32 s1, s0, 31
	s_lshl_b64 s[0:1], s[0:1], 11
	v_mul_f32_e32 v1, v1, v17
	v_cvt_pk_bf16_f32 v1, v1, s0
	v_lshl_add_u64 v[18:19], v[6:7], 0, s[0:1]
	global_store_short v[18:19], v1, off
	v_cvt_pk_bf16_f32 v1, v15, s0
	v_lshl_add_u64 v[18:19], v[2:3], 0, s[0:1]
	global_store_short v[18:19], v1, off
.LBB0_565:
	v_add_f32_e32 v17, v106, v16
	v_sub_f32_e32 v16, v4, v17
	v_mul_f32_e32 v16, 0x3fb8aa3b, v16
	v_exp_f32_e32 v16, v16
	v_lshlrev_b32_e32 v1, 16, v51
	v_cndmask_b32_e64 v1, 0, v1, s[40:41]
	s_andn2_b64 vcc, exec, s[40:41]
	v_mul_f32_e32 v16, v16, v1
	s_cbranch_vccnz .LBB0_567
	v_sub_f32_e32 v1, v17, v4
	v_mul_f32_e32 v1, 0x3fb8aa3b, v1
	v_exp_f32_e32 v1, v1
	v_readlane_b32 s0, v254, 56
	v_readlane_b32 s1, v254, 57
	v_lshlrev_b32_e32 v18, 16, v36
	s_ashr_i32 s1, s0, 31
	s_lshl_b64 s[0:1], s[0:1], 11
	v_mul_f32_e32 v1, v1, v18
	v_cvt_pk_bf16_f32 v1, v1, s0
	v_lshl_add_u64 v[18:19], v[6:7], 0, s[0:1]
	global_store_short v[18:19], v1, off
	v_cvt_pk_bf16_f32 v1, v16, s0
	v_lshl_add_u64 v[18:19], v[2:3], 0, s[0:1]
	global_store_short v[18:19], v1, off
.LBB0_567:
	v_add_f32_e32 v18, v107, v17
	v_sub_f32_e32 v17, v4, v18
	v_mul_f32_e32 v17, 0x3fb8aa3b, v17
	v_exp_f32_e32 v17, v17
	v_lshlrev_b32_e32 v1, 16, v52
	v_cndmask_b32_e64 v1, 0, v1, s[36:37]
	s_andn2_b64 vcc, exec, s[36:37]
	v_mul_f32_e32 v17, v17, v1
	s_cbranch_vccnz .LBB0_569
	v_sub_f32_e32 v1, v18, v4
	v_mul_f32_e32 v1, 0x3fb8aa3b, v1
	v_exp_f32_e32 v1, v1
	v_readlane_b32 s0, v254, 59
	v_readlane_b32 s1, v254, 60
	v_lshlrev_b32_e32 v19, 16, v37
	s_ashr_i32 s1, s0, 31
	s_lshl_b64 s[0:1], s[0:1], 11
	v_mul_f32_e32 v1, v1, v19
	v_cvt_pk_bf16_f32 v1, v1, s0
	v_lshl_add_u64 v[22:23], v[6:7], 0, s[0:1]
	global_store_short v[22:23], v1, off
	v_cvt_pk_bf16_f32 v1, v17, s0
	v_lshl_add_u64 v[22:23], v[2:3], 0, s[0:1]
	global_store_short v[22:23], v1, off
.LBB0_569:
	v_add_f32_e32 v19, v108, v18
	v_sub_f32_e32 v18, v4, v19
	v_mul_f32_e32 v18, 0x3fb8aa3b, v18
	v_exp_f32_e32 v18, v18
	v_lshlrev_b32_e32 v1, 16, v53
	v_cndmask_b32_e64 v1, 0, v1, s[34:35]
	s_andn2_b64 vcc, exec, s[34:35]
	v_mul_f32_e32 v18, v18, v1
	s_cbranch_vccnz .LBB0_571
	v_sub_f32_e32 v1, v19, v4
	v_mul_f32_e32 v1, 0x3fb8aa3b, v1
	v_exp_f32_e32 v1, v1
	v_readlane_b32 s0, v254, 62
	v_readlane_b32 s1, v254, 63
	v_lshlrev_b32_e32 v22, 16, v38
	s_ashr_i32 s1, s0, 31
	s_lshl_b64 s[0:1], s[0:1], 11
	v_mul_f32_e32 v1, v1, v22
	v_cvt_pk_bf16_f32 v1, v1, s0
	v_lshl_add_u64 v[22:23], v[6:7], 0, s[0:1]
	global_store_short v[22:23], v1, off
	v_cvt_pk_bf16_f32 v1, v18, s0
	v_lshl_add_u64 v[22:23], v[2:3], 0, s[0:1]
	global_store_short v[22:23], v1, off
.LBB0_571:
	v_add_f32_e32 v22, v109, v19
	v_sub_f32_e32 v19, v4, v22
	v_mul_f32_e32 v19, 0x3fb8aa3b, v19
	v_exp_f32_e32 v19, v19
	v_lshlrev_b32_e32 v1, 16, v54
	v_cndmask_b32_e64 v1, 0, v1, s[30:31]
	s_andn2_b64 vcc, exec, s[30:31]
	v_mul_f32_e32 v19, v19, v1
	s_cbranch_vccnz .LBB0_573
	v_sub_f32_e32 v1, v22, v4
	v_mul_f32_e32 v1, 0x3fb8aa3b, v1
	v_exp_f32_e32 v1, v1
	v_readlane_b32 s0, v253, 1
	v_readlane_b32 s1, v253, 2
	v_lshlrev_b32_e32 v23, 16, v39
	s_ashr_i32 s1, s0, 31
	s_lshl_b64 s[0:1], s[0:1], 11
	v_mul_f32_e32 v1, v1, v23
	v_cvt_pk_bf16_f32 v1, v1, s0
	v_lshl_add_u64 v[24:25], v[6:7], 0, s[0:1]
	global_store_short v[24:25], v1, off
	v_cvt_pk_bf16_f32 v1, v19, s0
	v_lshl_add_u64 v[24:25], v[2:3], 0, s[0:1]
	global_store_short v[24:25], v1, off
.LBB0_573:
	v_add_f32_e32 v23, v110, v22
	v_sub_f32_e32 v22, v4, v23
	v_mul_f32_e32 v22, 0x3fb8aa3b, v22
	v_exp_f32_e32 v22, v22
	v_lshlrev_b32_e32 v1, 16, v55
	v_cndmask_b32_e64 v1, 0, v1, s[24:25]
	s_andn2_b64 vcc, exec, s[24:25]
	v_mul_f32_e32 v22, v22, v1
	s_cbranch_vccnz .LBB0_575
	v_sub_f32_e32 v1, v23, v4
	v_mul_f32_e32 v1, 0x3fb8aa3b, v1
	v_exp_f32_e32 v1, v1
	v_readlane_b32 s0, v253, 4
	v_readlane_b32 s1, v253, 5
	v_lshlrev_b32_e32 v24, 16, v40
	s_ashr_i32 s1, s0, 31
	s_lshl_b64 s[0:1], s[0:1], 11
	v_mul_f32_e32 v1, v1, v24
	v_cvt_pk_bf16_f32 v1, v1, s0
	v_lshl_add_u64 v[24:25], v[6:7], 0, s[0:1]
	global_store_short v[24:25], v1, off
	v_cvt_pk_bf16_f32 v1, v22, s0
	v_lshl_add_u64 v[24:25], v[2:3], 0, s[0:1]
	global_store_short v[24:25], v1, off
.LBB0_575:
	v_add_f32_e32 v23, v111, v23
	v_sub_f32_e32 v24, v4, v23
	v_mul_f32_e32 v24, 0x3fb8aa3b, v24
	v_exp_f32_e32 v24, v24
	v_lshlrev_b32_e32 v1, 16, v56
	v_cndmask_b32_e64 v1, 0, v1, s[44:45]
	s_andn2_b64 vcc, exec, s[44:45]
	v_mul_f32_e32 v24, v24, v1
	s_cbranch_vccnz .LBB0_577
	v_sub_f32_e32 v1, v23, v4
	v_mul_f32_e32 v1, 0x3fb8aa3b, v1
	v_exp_f32_e32 v1, v1
	v_readlane_b32 s0, v253, 8
	v_readlane_b32 s1, v253, 9
	v_lshlrev_b32_e32 v25, 16, v41
	s_ashr_i32 s1, s0, 31
	s_lshl_b64 s[0:1], s[0:1], 11
	v_mul_f32_e32 v1, v1, v25
	v_cvt_pk_bf16_f32 v1, v1, s0
	v_lshl_add_u64 v[36:37], v[6:7], 0, s[0:1]
	global_store_short v[36:37], v1, off
	v_cvt_pk_bf16_f32 v1, v24, s0
	v_lshl_add_u64 v[36:37], v[2:3], 0, s[0:1]
	global_store_short v[36:37], v1, off
.LBB0_577:
	v_mul_f32_e32 v1, v13, v22
	v_mul_f32_e32 v18, v13, v18
	v_mul_f32_e32 v19, v13, v19
	v_mul_f32_e32 v16, v13, v16
	v_mul_f32_e32 v17, v13, v17
	v_mul_f32_e32 v14, v13, v14
	v_mul_f32_e32 v15, v13, v15
	v_mul_f32_e32 v24, v13, v24
	v_cvt_pk_bf16_f32 v14, v14, v15
	v_cvt_pk_bf16_f32 v15, v16, v17
	v_cvt_pk_bf16_f32 v16, v18, v19
	v_cvt_pk_bf16_f32 v17, v1, v24
	global_store_dwordx4 v[10:11], v[14:17], off offset:32
	v_lshlrev_b32_e32 v22, 16, v49
	v_cndmask_b32_e64 v22, 0, v22, s[26:27]
	v_add_f32_e32 v15, v112, v23
	v_sub_f32_e32 v1, v4, v15
	v_mul_f32_e32 v1, 0x3fb8aa3b, v1
	v_exp_f32_e32 v1, v1
	s_andn2_b64 vcc, exec, s[26:27]
	v_mul_f32_e32 v14, v1, v22
	s_cbranch_vccnz .LBB0_579
	v_sub_f32_e32 v1, v15, v4
	v_mul_f32_e32 v1, 0x3fb8aa3b, v1
	v_exp_f32_e32 v1, v1
	v_readlane_b32 s0, v253, 12
	v_readlane_b32 s1, v253, 13
	v_lshlrev_b32_e32 v16, 16, v28
	s_ashr_i32 s1, s0, 31
	s_lshl_b64 s[0:1], s[0:1], 11
	v_mul_f32_e32 v1, v1, v16
	v_cvt_pk_bf16_f32 v1, v1, s0
	v_lshl_add_u64 v[16:17], v[6:7], 0, s[0:1]
	global_store_short v[16:17], v1, off
	v_cvt_pk_bf16_f32 v1, v14, s0
	v_lshl_add_u64 v[16:17], v[2:3], 0, s[0:1]
	global_store_short v[16:17], v1, off
.LBB0_579:
	v_add_f32_e32 v16, v113, v15
	v_sub_f32_e32 v15, v4, v16
	v_mul_f32_e32 v15, 0x3fb8aa3b, v15
	v_exp_f32_e32 v15, v15
	v_lshlrev_b32_e32 v1, 16, v44
	v_cndmask_b32_e64 v1, 0, v1, s[28:29]
	s_andn2_b64 vcc, exec, s[28:29]
	v_mul_f32_e32 v15, v15, v1
	s_cbranch_vccnz .LBB0_581
	v_sub_f32_e32 v1, v16, v4
	v_mul_f32_e32 v1, 0x3fb8aa3b, v1
	v_exp_f32_e32 v1, v1
	v_readlane_b32 s0, v253, 14
	v_readlane_b32 s1, v253, 15
	v_lshlrev_b32_e32 v17, 16, v29
	s_ashr_i32 s1, s0, 31
	s_lshl_b64 s[0:1], s[0:1], 11
	v_mul_f32_e32 v1, v1, v17
	v_cvt_pk_bf16_f32 v1, v1, s0
	v_lshl_add_u64 v[18:19], v[6:7], 0, s[0:1]
	global_store_short v[18:19], v1, off
	v_cvt_pk_bf16_f32 v1, v15, s0
	v_lshl_add_u64 v[18:19], v[2:3], 0, s[0:1]
	global_store_short v[18:19], v1, off
.LBB0_581:
	v_add_f32_e32 v17, v114, v16
	v_sub_f32_e32 v16, v4, v17
	v_mul_f32_e32 v16, 0x3fb8aa3b, v16
	v_exp_f32_e32 v16, v16
	v_lshlrev_b32_e32 v1, 16, v45
	v_cndmask_b32_e64 v1, 0, v1, s[22:23]
	s_andn2_b64 vcc, exec, s[22:23]
	v_mul_f32_e32 v16, v16, v1
	s_cbranch_vccnz .LBB0_583
	v_sub_f32_e32 v1, v17, v4
	v_mul_f32_e32 v1, 0x3fb8aa3b, v1
	v_exp_f32_e32 v1, v1
	v_readlane_b32 s0, v253, 16
	v_readlane_b32 s1, v253, 17
	v_lshlrev_b32_e32 v18, 16, v30
	s_ashr_i32 s1, s0, 31
	s_lshl_b64 s[0:1], s[0:1], 11
	v_mul_f32_e32 v1, v1, v18
	v_cvt_pk_bf16_f32 v1, v1, s0
	v_lshl_add_u64 v[18:19], v[6:7], 0, s[0:1]
	global_store_short v[18:19], v1, off
	v_cvt_pk_bf16_f32 v1, v16, s0
	v_lshl_add_u64 v[18:19], v[2:3], 0, s[0:1]
	global_store_short v[18:19], v1, off
.LBB0_583:
	v_add_f32_e32 v18, v115, v17
	v_sub_f32_e32 v17, v4, v18
	v_mul_f32_e32 v17, 0x3fb8aa3b, v17
	v_exp_f32_e32 v17, v17
	v_lshlrev_b32_e32 v1, 16, v46
	v_cndmask_b32_e64 v1, 0, v1, s[10:11]
	s_andn2_b64 vcc, exec, s[10:11]
	v_mul_f32_e32 v17, v17, v1
	s_cbranch_vccnz .LBB0_585
	v_sub_f32_e32 v1, v18, v4
	v_mul_f32_e32 v1, 0x3fb8aa3b, v1
	v_exp_f32_e32 v1, v1
	v_readlane_b32 s0, v253, 18
	v_readlane_b32 s1, v253, 19
	v_lshlrev_b32_e32 v19, 16, v31
	s_ashr_i32 s1, s0, 31
	s_lshl_b64 s[0:1], s[0:1], 11
	v_mul_f32_e32 v1, v1, v19
	v_cvt_pk_bf16_f32 v1, v1, s0
	v_lshl_add_u64 v[22:23], v[6:7], 0, s[0:1]
	global_store_short v[22:23], v1, off
	v_cvt_pk_bf16_f32 v1, v17, s0
	v_lshl_add_u64 v[22:23], v[2:3], 0, s[0:1]
	global_store_short v[22:23], v1, off
.LBB0_585:
	v_add_f32_e32 v19, v116, v18
	v_sub_f32_e32 v18, v4, v19
	v_mul_f32_e32 v18, 0x3fb8aa3b, v18
	v_exp_f32_e32 v18, v18
	v_lshlrev_b32_e32 v1, 16, v47
	v_cndmask_b32_e64 v1, 0, v1, s[18:19]
	s_andn2_b64 vcc, exec, s[18:19]
	v_mul_f32_e32 v18, v18, v1
	s_cbranch_vccnz .LBB0_587
	v_sub_f32_e32 v1, v19, v4
	v_mul_f32_e32 v1, 0x3fb8aa3b, v1
	v_exp_f32_e32 v1, v1
	v_readlane_b32 s0, v253, 20
	v_readlane_b32 s1, v253, 21
	v_lshlrev_b32_e32 v22, 16, v32
	s_ashr_i32 s1, s0, 31
	s_lshl_b64 s[0:1], s[0:1], 11
	v_mul_f32_e32 v1, v1, v22
	v_cvt_pk_bf16_f32 v1, v1, s0
	v_lshl_add_u64 v[22:23], v[6:7], 0, s[0:1]
	global_store_short v[22:23], v1, off
	v_cvt_pk_bf16_f32 v1, v18, s0
	v_lshl_add_u64 v[22:23], v[2:3], 0, s[0:1]
	global_store_short v[22:23], v1, off
.LBB0_587:
	v_add_f32_e32 v22, v117, v19
	v_sub_f32_e32 v19, v4, v22
	v_mul_f32_e32 v19, 0x3fb8aa3b, v19
	v_exp_f32_e32 v19, v19
	v_lshlrev_b32_e32 v1, 16, v48
	v_cndmask_b32_e64 v1, 0, v1, s[20:21]
	s_andn2_b64 vcc, exec, s[20:21]
	v_mul_f32_e32 v19, v19, v1
	s_cbranch_vccnz .LBB0_589
	v_sub_f32_e32 v1, v22, v4
	v_mul_f32_e32 v1, 0x3fb8aa3b, v1
	v_exp_f32_e32 v1, v1
	v_readlane_b32 s0, v253, 22
	v_readlane_b32 s1, v253, 23
	v_lshlrev_b32_e32 v23, 16, v33
	s_ashr_i32 s1, s0, 31
	s_lshl_b64 s[0:1], s[0:1], 11
	v_mul_f32_e32 v1, v1, v23
	v_cvt_pk_bf16_f32 v1, v1, s0
	v_lshl_add_u64 v[24:25], v[6:7], 0, s[0:1]
	global_store_short v[24:25], v1, off
	v_cvt_pk_bf16_f32 v1, v19, s0
	v_lshl_add_u64 v[24:25], v[2:3], 0, s[0:1]
	global_store_short v[24:25], v1, off
.LBB0_589:
	v_add_f32_e32 v23, v118, v22
	v_sub_f32_e32 v22, v4, v23
	v_mul_f32_e32 v22, 0x3fb8aa3b, v22
	v_exp_f32_e32 v22, v22
	v_lshlrev_b32_e32 v1, 16, v42
	v_cndmask_b32_e64 v1, 0, v1, s[12:13]
	s_andn2_b64 vcc, exec, s[12:13]
	v_mul_f32_e32 v22, v22, v1
	s_cbranch_vccnz .LBB0_591
	v_sub_f32_e32 v1, v23, v4
	v_mul_f32_e32 v1, 0x3fb8aa3b, v1
	v_exp_f32_e32 v1, v1
	v_readlane_b32 s0, v253, 24
	v_readlane_b32 s1, v253, 25
	v_lshlrev_b32_e32 v24, 16, v27
	s_ashr_i32 s1, s0, 31
	s_lshl_b64 s[0:1], s[0:1], 11
	v_mul_f32_e32 v1, v1, v24
	v_cvt_pk_bf16_f32 v1, v1, s0
	v_lshl_add_u64 v[24:25], v[6:7], 0, s[0:1]
	global_store_short v[24:25], v1, off
	v_cvt_pk_bf16_f32 v1, v22, s0
	v_lshl_add_u64 v[24:25], v[2:3], 0, s[0:1]
	global_store_short v[24:25], v1, off
.LBB0_591:
	v_lshlrev_b32_e32 v1, 16, v21
	v_add_f32_e32 v21, v12, v23
	v_sub_f32_e32 v12, v4, v21
	v_mul_f32_e32 v12, 0x3fb8aa3b, v12
	v_exp_f32_e32 v12, v12
	v_cndmask_b32_e64 v1, 0, v1, s[4:5]
	s_andn2_b64 vcc, exec, s[4:5]
	v_mul_f32_e32 v12, v12, v1
	s_cbranch_vccnz .LBB0_593
	v_sub_f32_e32 v1, v21, v4
	v_mul_f32_e32 v1, 0x3fb8aa3b, v1
	v_exp_f32_e32 v1, v1
	v_readlane_b32 s0, v253, 26
	v_readlane_b32 s1, v253, 27
	v_lshlrev_b32_e32 v20, 16, v20
	s_ashr_i32 s1, s0, 31
	s_lshl_b64 s[0:1], s[0:1], 11
	v_mul_f32_e32 v1, v1, v20
	v_cvt_pk_bf16_f32 v1, v1, s0
	v_lshl_add_u64 v[6:7], v[6:7], 0, s[0:1]
	global_store_short v[6:7], v1, off
	v_cvt_pk_bf16_f32 v1, v12, s0
	v_lshl_add_u64 v[2:3], v[2:3], 0, s[0:1]
	global_store_short v[2:3], v1, off
.LBB0_593:
	v_mul_f32_e32 v1, v13, v22
	v_mul_f32_e32 v2, v13, v18
	v_mul_f32_e32 v3, v13, v19
	v_mul_f32_e32 v6, v13, v16
	v_mul_f32_e32 v7, v13, v17
	v_mul_f32_e32 v14, v13, v14
	v_mul_f32_e32 v15, v13, v15
	v_mul_f32_e32 v16, v13, v12
	v_cvt_pk_bf16_f32 v12, v14, v15
	v_cvt_pk_bf16_f32 v13, v6, v7
	v_cvt_pk_bf16_f32 v14, v2, v3
	v_cvt_pk_bf16_f32 v15, v1, v16
	s_andn2_b64 vcc, exec, s[6:7]
	global_store_dwordx4 v[10:11], v[12:15], off offset:48
	s_cbranch_vccnz .LBB0_524
	v_mul_f32_e32 v4, 0x3fb8aa3b, v4
	v_readlane_b32 s0, v253, 45
	v_lshlrev_b64 v[2:3], 2, v[8:9]
	v_mul_f32_e32 v1, 0x3fb8aa3b, v5
	v_exp_f32_e32 v6, v4
	v_readlane_b32 s1, v253, 46
	v_exp_f32_e32 v1, v1
	s_nop 0
	v_lshl_add_u64 v[4:5], s[0:1], 0, v[2:3]
	v_readlane_b32 s0, v251, 30
	v_readlane_b32 s1, v251, 31
	s_nop 1
	v_lshl_add_u64 v[2:3], s[0:1], 0, v[2:3]
	global_store_dword v[2:3], v6, off
	global_store_dword v[4:5], v1, off
	s_branch .LBB0_524
